# GEMM loops: LDS-DMA tile loads through scalar base + 32-bit lane offset (no 64-bit VALU address add per piece)
# speedup vs baseline: 1.0095x; 1.0004x over previous
; #define PG8_STAGE(bufoff, gbase, voff) do { _Pragma("unroll") for (int _i = 0; _i < 2; ++_i) \
;         __builtin_amdgcn_global_load_lds((const unsigned*)((const char*)(gbase) + (voff)[_i]), (LAS unsigned*)(lds + (bufoff) + ldsw + _i * 8192), 16, 0, 0); } while (0)
; #define PG8_LDA(dst, b, h) do { _Pragma("unroll") for (int m = 0; m < 4; ++m) _Pragma("unroll") for (int k = 0; k < 2; ++k) dst[m][k] = *(const LAS bf16x8*)(lds + PG8_SA(b, h) + aoff + m * 2048 + k * 1024); } while (0)
; #define PG8_WAIT_V(n) asm volatile("s_waitcnt vmcnt(" #n ")" ::: "memory")
; #define PG8_BAR __builtin_amdgcn_s_barrier()
; template <class Epi, int LDA, int LDB, int KK>
; __device__ __forceinline__ void gemm_phase(int wv, LAS unsigned char* lds, const Gemm g, const StaticOrder& S, const Epi& E) {
;     ...
;           for (; t < tend; t += 2) {
;             const bool last = (t == nt - 2);
;             const char* a1 = cA + (size_t)(t + 1) * kstep;
;             const char* a2 = last ? nA : cA + (size_t)(t + 2) * kstep; const char* b2 = last ? nB : cB + (size_t)(t + 2) * kstep;
;             const char* a3 = a2 + kstep; const char* b3 = b2 + kstep;
;             PG8_LDB(B0, 0, 0); PG8_SCHED; PG8_LDA(At, 0, 0); PG8_STAGE(PG8_SA(1, 1), a1 + hstepA, voffA);
;             PG8_WAIT_L(8); PG8_BAR; PG8_WAIT_L(0); PG8_MMA(0, 0, At, B0); PG8_BAR; PG8_SCHED;
;             PG8_LDB(B1, 0, 1); PG8_STAGE(PG8_SB(0, 0), b2, voffB);
;             PG8_BAR; PG8_WAIT_L(0); PG8_MMA(0, 1, At, B1); PG8_BAR;
;             PG8_LDA(At, 0, 1); PG8_STAGE(PG8_SA(0, 0), a2, voffA);
;             PG8_BAR; PG8_WAIT_L(0); PG8_MMA(1, 0, At, B0); PG8_BAR; PG8_SCHED;
;             PG8_STAGE(PG8_SB(0, 1), b2 + hstepB, voffB);
;             PG8_WAIT_V(6); PG8_BAR; PG8_MMA(1, 1, At, B1); PG8_BAR;
;             PG8_LDB(B0, 1, 0); PG8_SCHED; PG8_LDA(At, 1, 0); PG8_STAGE(PG8_SA(0, 1), a2 + hstepA, voffA);
;             PG8_WAIT_L(8); PG8_BAR; PG8_WAIT_L(0); PG8_MMA(0, 0, At, B0); PG8_BAR; PG8_SCHED;
;             PG8_LDB(B1, 1, 1); PG8_STAGE(PG8_SB(1, 0), b3, voffB);
;             PG8_BAR; PG8_WAIT_L(0); PG8_MMA(0, 1, At, B1); PG8_BAR;
;             PG8_LDA(At, 1, 1); PG8_STAGE(PG8_SA(1, 0), a3, voffA);
;             PG8_BAR; PG8_WAIT_L(0); PG8_MMA(1, 0, At, B0); PG8_BAR; PG8_SCHED;
;             PG8_STAGE(PG8_SB(1, 1), b3 + hstepB, voffB);
;             PG8_WAIT_V(6); PG8_BAR; PG8_MMA(1, 1, At, B1); PG8_BAR;
.Lin_loop:
	s_add_u32 s34, s6, 0xfff80080
	s_addc_u32 s35, s7, -1
	s_cmp_eq_u32 s77, 28
	s_cselect_b32 s37, s23, s35
	s_cselect_b32 s36, s73, s34
	s_cselect_b32 s35, s21, s76
	s_cselect_b32 s34, s74, s75
	s_waitcnt lgkmcnt(0)
	v_mfma_f32_16x16x32_bf16 v[128:131], v[144:147], v[164:167], v[128:131]
	ds_read_b128 v[202:205], v197 offset:1024
	v_mfma_f32_16x16x32_bf16 v[124:127], v[152:155], v[164:167], v[124:127]
	ds_read_b128 v[206:209], v197 offset:3072
	v_mfma_f32_16x16x32_bf16 v[120:123], v[156:159], v[164:167], v[120:123]
	ds_read_b128 v[210:213], v197 offset:17408
	v_mfma_f32_16x16x32_bf16 v[116:119], v[160:163], v[164:167], v[116:119]
	ds_read_b128 v[214:217], v197 offset:19456
	v_mfma_f32_16x16x32_bf16 v[112:115], v[144:147], v[168:171], v[112:115]
	ds_read_b128 v[180:183], v151 offset:1024
	v_mfma_f32_16x16x32_bf16 v[108:111], v[152:155], v[168:171], v[108:111]
	ds_read_b128 v[184:187], v151 offset:3072
	v_mfma_f32_16x16x32_bf16 v[104:107], v[156:159], v[168:171], v[104:107]
	ds_read_b128 v[188:191], v151 offset:5120
	v_mfma_f32_16x16x32_bf16 v[96:99], v[160:163], v[168:171], v[96:99]
	ds_read_b128 v[192:195], v151 offset:7168
	v_mfma_f32_16x16x32_bf16 v[100:103], v[144:147], v[172:175], v[100:103]
	v_mfma_f32_16x16x32_bf16 v[92:95], v[152:155], v[172:175], v[92:95]
	v_mfma_f32_16x16x32_bf16 v[88:91], v[156:159], v[172:175], v[88:91]
	v_mfma_f32_16x16x32_bf16 v[84:87], v[160:163], v[172:175], v[84:87]
	v_mfma_f32_16x16x32_bf16 v[80:83], v[144:147], v[176:179], v[80:83]
	v_mfma_f32_16x16x32_bf16 v[76:79], v[152:155], v[176:179], v[76:79]
	v_mfma_f32_16x16x32_bf16 v[72:75], v[156:159], v[176:179], v[72:75]
	v_mfma_f32_16x16x32_bf16 v[68:71], v[160:163], v[176:179], v[68:71]
	s_waitcnt vmcnt(8) lgkmcnt(0)
	s_barrier
	v_mfma_f32_16x16x32_bf16 v[128:131], v[202:205], v[180:183], v[128:131]
	ds_read_b128 v[164:167], v151 offset:16384
	v_mfma_f32_16x16x32_bf16 v[124:127], v[206:209], v[180:183], v[124:127]
	ds_read_b128 v[168:171], v151 offset:18432
	v_mfma_f32_16x16x32_bf16 v[120:123], v[210:213], v[180:183], v[120:123]
	ds_read_b128 v[172:175], v151 offset:20480
	v_mfma_f32_16x16x32_bf16 v[116:119], v[214:217], v[180:183], v[116:119]
	ds_read_b128 v[176:179], v151 offset:22528
	v_mfma_f32_16x16x32_bf16 v[112:115], v[202:205], v[184:187], v[112:115]
	s_add_i32 m0, s31, 0x10000
	v_mfma_f32_16x16x32_bf16 v[108:111], v[206:209], v[184:187], v[108:111]
	global_load_lds_dwordx4 v132, s[34:35]
	v_mfma_f32_16x16x32_bf16 v[104:107], v[210:213], v[184:187], v[104:107]
	v_mfma_f32_16x16x32_bf16 v[96:99], v[214:217], v[184:187], v[96:99]
	s_add_i32 m0, s31, 0x12000
	v_mfma_f32_16x16x32_bf16 v[100:103], v[202:205], v[188:191], v[100:103]
	global_load_lds_dwordx4 v136, s[34:35]
	v_mfma_f32_16x16x32_bf16 v[92:95], v[206:209], v[188:191], v[92:95]
	v_mfma_f32_16x16x32_bf16 v[88:91], v[210:213], v[188:191], v[88:91]
	s_mov_b32 m0, s31
	v_mfma_f32_16x16x32_bf16 v[84:87], v[214:217], v[188:191], v[84:87]
	global_load_lds_dwordx4 v0, s[36:37]
	v_mfma_f32_16x16x32_bf16 v[80:83], v[202:205], v[192:195], v[80:83]
	v_mfma_f32_16x16x32_bf16 v[76:79], v[206:209], v[192:195], v[76:79]
	v_mfma_f32_16x16x32_bf16 v[72:75], v[210:213], v[192:195], v[72:75]
	v_mfma_f32_16x16x32_bf16 v[68:71], v[214:217], v[192:195], v[68:71]
	s_waitcnt lgkmcnt(0)
	v_mfma_f32_16x16x32_bf16 v[64:67], v[144:147], v[164:167], v[64:67]
	ds_read_b128 v[180:183], v151 offset:17408
	v_mfma_f32_16x16x32_bf16 v[60:63], v[152:155], v[164:167], v[60:63]
	ds_read_b128 v[184:187], v151 offset:19456
	v_mfma_f32_16x16x32_bf16 v[56:59], v[156:159], v[164:167], v[56:59]
	ds_read_b128 v[188:191], v151 offset:21504
	v_mfma_f32_16x16x32_bf16 v[52:55], v[160:163], v[164:167], v[52:55]
	ds_read_b128 v[192:195], v151 offset:23552
	v_mfma_f32_16x16x32_bf16 v[48:51], v[144:147], v[168:171], v[48:51]
	s_add_i32 m0, s31, 0x2000
	v_mfma_f32_16x16x32_bf16 v[44:47], v[152:155], v[168:171], v[44:47]
	global_load_lds_dwordx4 v134, s[36:37]
	v_mfma_f32_16x16x32_bf16 v[40:43], v[156:159], v[168:171], v[40:43]
	v_mfma_f32_16x16x32_bf16 v[32:35], v[160:163], v[168:171], v[32:35]
	s_add_u32 s98, s34, 0x80000
	s_addc_u32 s99, s35, 0
	s_add_i32 m0, s31, 0x14000
	v_mfma_f32_16x16x32_bf16 v[36:39], v[144:147], v[172:175], v[36:39]
	global_load_lds_dwordx4 v132, s[98:99]
	v_mfma_f32_16x16x32_bf16 v[28:31], v[152:155], v[172:175], v[28:31]
	v_mfma_f32_16x16x32_bf16 v[24:27], v[156:159], v[172:175], v[24:27]
	s_add_i32 m0, s31, 0x16000
	v_mfma_f32_16x16x32_bf16 v[20:23], v[160:163], v[172:175], v[20:23]
	global_load_lds_dwordx4 v136, s[98:99]
	v_mfma_f32_16x16x32_bf16 v[16:19], v[144:147], v[176:179], v[16:19]
	v_mfma_f32_16x16x32_bf16 v[12:15], v[152:155], v[176:179], v[12:15]
	v_mfma_f32_16x16x32_bf16 v[8:11], v[156:159], v[176:179], v[8:11]
	v_mfma_f32_16x16x32_bf16 v[4:7], v[160:163], v[176:179], v[4:7]
	s_waitcnt vmcnt(8) lgkmcnt(0)
	s_barrier
; #define PG8_STAGE(bufoff, gbase, voff) do { _Pragma("unroll") for (int _i = 0; _i < 2; ++_i) \
;         __builtin_amdgcn_global_load_lds((const unsigned*)((const char*)(gbase) + (voff)[_i]), (LAS unsigned*)(lds + (bufoff) + ldsw + _i * 8192), 16, 0, 0); } while (0)
; #define PG8_LDA(dst, b, h) do { _Pragma("unroll") for (int m = 0; m < 4; ++m) _Pragma("unroll") for (int k = 0; k < 2; ++k) dst[m][k] = *(const LAS bf16x8*)(lds + PG8_SA(b, h) + aoff + m * 2048 + k * 1024); } while (0)
; #define PG8_LDB(dst, b, h) do { _Pragma("unroll") for (int n = 0; n < 2; ++n) _Pragma("unroll") for (int k = 0; k < 2; ++k) dst[n][k] = *(const LAS bf16x8*)(lds + PG8_SB(b, h) + boff + n * 2048 + k * 1024); } while (0)
; #define PG8_WAIT_V(n) asm volatile("s_waitcnt vmcnt(" #n ")" ::: "memory")
; #define PG8_WAIT_L(n) asm volatile("s_waitcnt lgkmcnt(" #n ")" ::: "memory")
; #define PG8_BAR __builtin_amdgcn_s_barrier()
; #define PG8_SCHED __builtin_amdgcn_sched_barrier(0)
; template <class Epi, int LDA, int LDB, int KK>
; __device__ __forceinline__ void gemm_phase(int wv, LAS unsigned char* lds, const Gemm g, const StaticOrder& S, const Epi& E) {
;     ...
;             PG8_LDB(B0, 0, 0); PG8_SCHED; PG8_LDA(At, 0, 0); PG8_STAGE(PG8_SA(1, 1), a1 + hstepA, voffA);
;             PG8_WAIT_L(8); PG8_BAR; PG8_WAIT_L(0); PG8_MMA(0, 0, At, B0); PG8_BAR; PG8_SCHED;
;             PG8_LDB(B1, 0, 1); PG8_STAGE(PG8_SB(0, 0), b2, voffB);
;             PG8_BAR; PG8_WAIT_L(0); PG8_MMA(0, 1, At, B1); PG8_BAR;
;             PG8_LDA(At, 0, 1); PG8_STAGE(PG8_SA(0, 0), a2, voffA);
;             PG8_BAR; PG8_WAIT_L(0); PG8_MMA(1, 0, At, B0); PG8_BAR; PG8_SCHED;
;             PG8_STAGE(PG8_SB(0, 1), b2 + hstepB, voffB);
;             PG8_WAIT_V(6); PG8_BAR; PG8_MMA(1, 1, At, B1); PG8_BAR;
;             PG8_LDB(B0, 1, 0); PG8_SCHED; PG8_LDA(At, 1, 0); PG8_STAGE(PG8_SA(0, 1), a2 + hstepA, voffA);
;             PG8_WAIT_L(8); PG8_BAR; PG8_WAIT_L(0); PG8_MMA(0, 0, At, B0); PG8_BAR; PG8_SCHED;
;             PG8_LDB(B1, 1, 1); PG8_STAGE(PG8_SB(1, 0), b3, voffB);
;             PG8_BAR; PG8_WAIT_L(0); PG8_MMA(0, 1, At, B1); PG8_BAR;
;             PG8_LDA(At, 1, 1); PG8_STAGE(PG8_SA(1, 0), a3, voffA);
;             PG8_BAR; PG8_WAIT_L(0); PG8_MMA(1, 0, At, B0); PG8_BAR; PG8_SCHED;
;             PG8_STAGE(PG8_SB(1, 1), b3 + hstepB, voffB);
;             PG8_WAIT_V(6); PG8_BAR; PG8_MMA(1, 1, At, B1); PG8_BAR;
	v_mfma_f32_16x16x32_bf16 v[64:67], v[202:205], v[180:183], v[64:67]
	ds_read_b128 v[144:147], v197 offset:32768
	v_mfma_f32_16x16x32_bf16 v[60:63], v[206:209], v[180:183], v[60:63]
	ds_read_b128 v[152:155], v197 offset:34816
	v_mfma_f32_16x16x32_bf16 v[56:59], v[210:213], v[180:183], v[56:59]
	ds_read_b128 v[156:159], v197 offset:49152
	v_mfma_f32_16x16x32_bf16 v[52:55], v[214:217], v[180:183], v[52:55]
	ds_read_b128 v[160:163], v197 offset:51200
	v_mfma_f32_16x16x32_bf16 v[48:51], v[202:205], v[184:187], v[48:51]
	ds_read_b128 v[164:167], v151 offset:32768
	v_mfma_f32_16x16x32_bf16 v[44:47], v[206:209], v[184:187], v[44:47]
	ds_read_b128 v[168:171], v151 offset:34816
	v_mfma_f32_16x16x32_bf16 v[40:43], v[210:213], v[184:187], v[40:43]
	ds_read_b128 v[172:175], v151 offset:36864
	v_mfma_f32_16x16x32_bf16 v[32:35], v[214:217], v[184:187], v[32:35]
	ds_read_b128 v[176:179], v151 offset:38912
	v_mfma_f32_16x16x32_bf16 v[36:39], v[202:205], v[188:191], v[36:39]
	s_add_u32 s98, s36, 0x80000
	s_addc_u32 s99, s37, 0
	s_add_i32 m0, s31, 0x4000
	v_mfma_f32_16x16x32_bf16 v[28:31], v[206:209], v[188:191], v[28:31]
	global_load_lds_dwordx4 v0, s[98:99]
	v_mfma_f32_16x16x32_bf16 v[24:27], v[210:213], v[188:191], v[24:27]
	v_mfma_f32_16x16x32_bf16 v[20:23], v[214:217], v[188:191], v[20:23]
	s_add_i32 m0, s31, 0x6000
	v_mfma_f32_16x16x32_bf16 v[16:19], v[202:205], v[192:195], v[16:19]
	global_load_lds_dwordx4 v134, s[98:99]
	v_mfma_f32_16x16x32_bf16 v[12:15], v[206:209], v[192:195], v[12:15]
	v_mfma_f32_16x16x32_bf16 v[8:11], v[210:213], v[192:195], v[8:11]
	v_mfma_f32_16x16x32_bf16 v[4:7], v[214:217], v[192:195], v[4:7]
	s_add_u32 s34, s34, 0x80
	s_addc_u32 s35, s35, 0
	s_add_u32 s36, s36, 0x80
	s_addc_u32 s37, s37, 0
	s_waitcnt lgkmcnt(0)
	v_mfma_f32_16x16x32_bf16 v[128:131], v[144:147], v[164:167], v[128:131]
	ds_read_b128 v[202:205], v197 offset:33792
	v_mfma_f32_16x16x32_bf16 v[124:127], v[152:155], v[164:167], v[124:127]
	ds_read_b128 v[206:209], v197 offset:35840
	v_mfma_f32_16x16x32_bf16 v[120:123], v[156:159], v[164:167], v[120:123]
	ds_read_b128 v[210:213], v197 offset:50176
	v_mfma_f32_16x16x32_bf16 v[116:119], v[160:163], v[164:167], v[116:119]
	ds_read_b128 v[214:217], v197 offset:52224
	v_mfma_f32_16x16x32_bf16 v[112:115], v[144:147], v[168:171], v[112:115]
	ds_read_b128 v[180:183], v151 offset:33792
	v_mfma_f32_16x16x32_bf16 v[108:111], v[152:155], v[168:171], v[108:111]
	ds_read_b128 v[184:187], v151 offset:35840
	v_mfma_f32_16x16x32_bf16 v[104:107], v[156:159], v[168:171], v[104:107]
	ds_read_b128 v[188:191], v151 offset:37888
	v_mfma_f32_16x16x32_bf16 v[96:99], v[160:163], v[168:171], v[96:99]
	ds_read_b128 v[192:195], v151 offset:39936
	v_mfma_f32_16x16x32_bf16 v[100:103], v[144:147], v[172:175], v[100:103]
	v_mfma_f32_16x16x32_bf16 v[92:95], v[152:155], v[172:175], v[92:95]
	v_mfma_f32_16x16x32_bf16 v[88:91], v[156:159], v[172:175], v[88:91]
	v_mfma_f32_16x16x32_bf16 v[84:87], v[160:163], v[172:175], v[84:87]
	v_mfma_f32_16x16x32_bf16 v[80:83], v[144:147], v[176:179], v[80:83]
	v_mfma_f32_16x16x32_bf16 v[76:79], v[152:155], v[176:179], v[76:79]
	v_mfma_f32_16x16x32_bf16 v[72:75], v[156:159], v[176:179], v[72:75]
	v_mfma_f32_16x16x32_bf16 v[68:71], v[160:163], v[176:179], v[68:71]
	s_waitcnt vmcnt(8) lgkmcnt(0)
	s_barrier
	v_mfma_f32_16x16x32_bf16 v[128:131], v[202:205], v[180:183], v[128:131]
	ds_read_b128 v[164:167], v151 offset:49152
	v_mfma_f32_16x16x32_bf16 v[124:127], v[206:209], v[180:183], v[124:127]
	ds_read_b128 v[168:171], v151 offset:51200
	v_mfma_f32_16x16x32_bf16 v[120:123], v[210:213], v[180:183], v[120:123]
	ds_read_b128 v[172:175], v151 offset:53248
	v_mfma_f32_16x16x32_bf16 v[116:119], v[214:217], v[180:183], v[116:119]
	ds_read_b128 v[176:179], v151 offset:55296
	v_mfma_f32_16x16x32_bf16 v[112:115], v[202:205], v[184:187], v[112:115]
	s_add_i32 m0, s31, 0x18000
	v_mfma_f32_16x16x32_bf16 v[108:111], v[206:209], v[184:187], v[108:111]
	global_load_lds_dwordx4 v132, s[34:35]
	v_mfma_f32_16x16x32_bf16 v[104:107], v[210:213], v[184:187], v[104:107]
	v_mfma_f32_16x16x32_bf16 v[96:99], v[214:217], v[184:187], v[96:99]
	s_add_i32 m0, s31, 0x1a000
	v_mfma_f32_16x16x32_bf16 v[100:103], v[202:205], v[188:191], v[100:103]
	global_load_lds_dwordx4 v136, s[34:35]
	v_mfma_f32_16x16x32_bf16 v[92:95], v[206:209], v[188:191], v[92:95]
	v_mfma_f32_16x16x32_bf16 v[88:91], v[210:213], v[188:191], v[88:91]
	s_add_i32 m0, s31, 0x8000
	v_mfma_f32_16x16x32_bf16 v[84:87], v[214:217], v[188:191], v[84:87]
	global_load_lds_dwordx4 v0, s[36:37]
	v_mfma_f32_16x16x32_bf16 v[80:83], v[202:205], v[192:195], v[80:83]
	v_mfma_f32_16x16x32_bf16 v[76:79], v[206:209], v[192:195], v[76:79]
	v_mfma_f32_16x16x32_bf16 v[72:75], v[210:213], v[192:195], v[72:75]
	v_mfma_f32_16x16x32_bf16 v[68:71], v[214:217], v[192:195], v[68:71]
	s_waitcnt lgkmcnt(0)
	v_mfma_f32_16x16x32_bf16 v[64:67], v[144:147], v[164:167], v[64:67]
	ds_read_b128 v[180:183], v151 offset:50176
	v_mfma_f32_16x16x32_bf16 v[60:63], v[152:155], v[164:167], v[60:63]
	ds_read_b128 v[184:187], v151 offset:52224
	v_mfma_f32_16x16x32_bf16 v[56:59], v[156:159], v[164:167], v[56:59]
	ds_read_b128 v[188:191], v151 offset:54272
	v_mfma_f32_16x16x32_bf16 v[52:55], v[160:163], v[164:167], v[52:55]
	ds_read_b128 v[192:195], v151 offset:56320
	v_mfma_f32_16x16x32_bf16 v[48:51], v[144:147], v[168:171], v[48:51]
	s_add_i32 m0, s31, 0xa000
	v_mfma_f32_16x16x32_bf16 v[44:47], v[152:155], v[168:171], v[44:47]
	global_load_lds_dwordx4 v134, s[36:37]
	v_mfma_f32_16x16x32_bf16 v[40:43], v[156:159], v[168:171], v[40:43]
	v_mfma_f32_16x16x32_bf16 v[32:35], v[160:163], v[168:171], v[32:35]
	s_add_u32 s98, s34, 0x80000
	s_addc_u32 s99, s35, 0
	s_add_i32 m0, s31, 0x1c000
	v_mfma_f32_16x16x32_bf16 v[36:39], v[144:147], v[172:175], v[36:39]
	global_load_lds_dwordx4 v132, s[98:99]
	v_mfma_f32_16x16x32_bf16 v[28:31], v[152:155], v[172:175], v[28:31]
	v_mfma_f32_16x16x32_bf16 v[24:27], v[156:159], v[172:175], v[24:27]
	s_add_i32 m0, s31, 0x1e000
	v_mfma_f32_16x16x32_bf16 v[20:23], v[160:163], v[172:175], v[20:23]
	global_load_lds_dwordx4 v136, s[98:99]
	v_mfma_f32_16x16x32_bf16 v[16:19], v[144:147], v[176:179], v[16:19]
	v_mfma_f32_16x16x32_bf16 v[12:15], v[152:155], v[176:179], v[12:15]
	v_mfma_f32_16x16x32_bf16 v[8:11], v[156:159], v[176:179], v[8:11]
	v_mfma_f32_16x16x32_bf16 v[4:7], v[160:163], v[176:179], v[4:7]
	s_waitcnt vmcnt(8) lgkmcnt(0)
	s_barrier
; #define LAS __attribute__((address_space(3)))
; #define PG8_STAGE(bufoff, gbase, voff) do { _Pragma("unroll") for (int _i = 0; _i < 2; ++_i) \
;         __builtin_amdgcn_global_load_lds((const unsigned*)((const char*)(gbase) + (voff)[_i]), (LAS unsigned*)(lds + (bufoff) + ldsw + _i * 8192), 16, 0, 0); } while (0)
; #define PG8_LDA(dst, b, h) do { _Pragma("unroll") for (int m = 0; m < 4; ++m) _Pragma("unroll") for (int k = 0; k < 2; ++k) dst[m][k] = *(const LAS bf16x8*)(lds + PG8_SA(b, h) + aoff + m * 2048 + k * 1024); } while (0)
; #define PG8_MMA(ai, bj, At, Bt) do { __builtin_amdgcn_s_setprio(1); _Pragma("unroll") for (int m = 0; m < 4; ++m) _Pragma("unroll") for (int n = 0; n < 2; ++n) _Pragma("unroll") for (int k = 0; k < 2; ++k) \
;         acc[ai][bj][m][n] = __builtin_amdgcn_mfma_f32_16x16x32_bf16(Bt[n][k], At[m][k], acc[ai][bj][m][n], 0, 0, 0); __builtin_amdgcn_s_setprio(0); } while (0)
; #define PG8_WAIT_V(n) asm volatile("s_waitcnt vmcnt(" #n ")" ::: "memory")
; #define PG8_WAIT_L(n) asm volatile("s_waitcnt lgkmcnt(" #n ")" ::: "memory")
; #define PG8_BAR __builtin_amdgcn_s_barrier()
; #define PG8_SCHED __builtin_amdgcn_sched_barrier(0)
; template <class Epi, int LDA, int LDB, int KK>
; __device__ __forceinline__ void gemm_phase(int wv, LAS unsigned char* lds, const Gemm g, const StaticOrder& S, const Epi& E) {
;     ...
;             PG8_LDA(At, 1, 1); PG8_STAGE(PG8_SA(1, 0), a3, voffA);
;             PG8_BAR; PG8_WAIT_L(0); PG8_MMA(1, 0, At, B0); PG8_BAR; PG8_SCHED;
;             PG8_STAGE(PG8_SB(1, 1), b3 + hstepB, voffB);
;             PG8_WAIT_V(6); PG8_BAR; PG8_MMA(1, 1, At, B1); PG8_BAR;
;           }
;           if constexpr (Epi::HAS_MID) { if (seg < Epi::NSEG - 1) E.mid(acc, cur, seg, wr, wc, fr, fq); }
;         }
;         E(acc, cur, wr, wc, fr, fq, (const LAS float*)(lds + 131072 + (ui % 3) * 1024));
;     __device__ __forceinline__ void operator()(AccT& acc, const pg8::Unit& u, int wr, int wc, int fr, int fq, const LAS float* rs) const {
;         int row0 = u.pm * 256 + wr * 64 + fr; asm volatile("" : "+v"(row0)); const int cb = wc * 32 + 8 * fq;
;         if (u.pn < 52) {
;             bf16_t* base = u.pn < 28 ? zA + u.pn * 256 : zG + (u.pn - 28) * 256; const int ld = u.pn < 28 ? NZA : NZG;
	v_mfma_f32_16x16x32_bf16 v[64:67], v[202:205], v[180:183], v[64:67]
	ds_read_b128 v[144:147], v197 offset:0
	v_mfma_f32_16x16x32_bf16 v[60:63], v[206:209], v[180:183], v[60:63]
	ds_read_b128 v[152:155], v197 offset:2048
	v_mfma_f32_16x16x32_bf16 v[56:59], v[210:213], v[180:183], v[56:59]
	ds_read_b128 v[156:159], v197 offset:16384
	v_mfma_f32_16x16x32_bf16 v[52:55], v[214:217], v[180:183], v[52:55]
	ds_read_b128 v[160:163], v197 offset:18432
	v_mfma_f32_16x16x32_bf16 v[48:51], v[202:205], v[184:187], v[48:51]
	ds_read_b128 v[164:167], v151 offset:0
	v_mfma_f32_16x16x32_bf16 v[44:47], v[206:209], v[184:187], v[44:47]
	ds_read_b128 v[168:171], v151 offset:2048
	v_mfma_f32_16x16x32_bf16 v[40:43], v[210:213], v[184:187], v[40:43]
	ds_read_b128 v[172:175], v151 offset:4096
	v_mfma_f32_16x16x32_bf16 v[32:35], v[214:217], v[184:187], v[32:35]
	ds_read_b128 v[176:179], v151 offset:6144
	v_mfma_f32_16x16x32_bf16 v[36:39], v[202:205], v[188:191], v[36:39]
	s_add_u32 s98, s36, 0x80000
	s_addc_u32 s99, s37, 0
	s_add_i32 m0, s31, 0xc000
	v_mfma_f32_16x16x32_bf16 v[28:31], v[206:209], v[188:191], v[28:31]
	global_load_lds_dwordx4 v0, s[98:99]
	v_mfma_f32_16x16x32_bf16 v[24:27], v[210:213], v[188:191], v[24:27]
	v_mfma_f32_16x16x32_bf16 v[20:23], v[214:217], v[188:191], v[20:23]
	s_add_i32 m0, s31, 0xe000
	v_mfma_f32_16x16x32_bf16 v[16:19], v[202:205], v[192:195], v[16:19]
	global_load_lds_dwordx4 v134, s[98:99]
	v_mfma_f32_16x16x32_bf16 v[12:15], v[206:209], v[192:195], v[12:15]
	v_mfma_f32_16x16x32_bf16 v[8:11], v[210:213], v[192:195], v[8:11]
	v_mfma_f32_16x16x32_bf16 v[4:7], v[214:217], v[192:195], v[4:7]
	s_add_i32 s77, s77, 2
	s_add_u32 s75, s75, 0x100
	s_addc_u32 s76, s76, 0
	s_add_u32 s6, s6, 0x100
	s_addc_u32 s7, s7, 0
	s_cmp_gt_u32 s77, 29
	s_cbranch_scc0 .Lin_loop
	s_waitcnt lgkmcnt(0)
	s_mul_hi_u32 s6, s71, 0xaaaaaaab
	s_lshr_b32 s6, s6, 1
	s_mul_i32 s6, s6, 3
	s_sub_i32 s6, s71, s6
	s_lshl_b32 s6, s6, 10
	s_add_i32 s21, s6, 0
	s_add_i32 s21, s21, 0x20000
	v_lshl_add_u32 v144, s30, 8, v149
	s_cmp_gt_i32 s28, 51
	s_mov_b64 s[6:7], -1
	s_cbranch_scc0 .LBB0_187
	s_and_saveexec_b64 s[6:7], s[8:9]
	s_cbranch_execz .LBB0_186
;     __device__ __forceinline__ void operator()(AccT& acc, const pg8::Unit& u, int wr, int wc, int fr, int fq, const LAS float* rs) const {
;     ...
;         } else if (wc == 0 && fq == 0) {
; #pragma unroll
;             for (int ai = 0; ai < 2; ++ai)
; #pragma unroll
;                 for (int m = 0; m < 4; ++m) {
;                     const int row = row0 + ai * 128 + m * 16; const float sc = rsqrtf(rs[ai * 128 + wr * 64 + m * 16 + fr] * (1.0f / D) + EPS);
;                     *(f32x4*)(gates + (size_t)row * 8) = acc[ai][0][m][0] * sc; *(f32x4*)(gates + (size_t)row * 8 + 4) = acc[ai][0][m][1] * sc;
;                 }
	s_lshl_b32 s23, s55, 2
	s_add_i32 s23, s21, s23
	v_lshl_add_u32 v162, v148, 2, s23
	ds_read2_b32 v[146:147], v162 offset1:16
	v_ashrrev_i32_e32 v145, 31, v144
	v_lshlrev_b64 v[152:153], 5, v[144:145]
	v_lshl_add_u64 v[156:157], s[18:19], 0, v[152:153]
	s_mov_b64 s[34:35], 0x1000
	s_waitcnt lgkmcnt(0)
	v_fmamk_f32 v145, v146, 0x3a000000, v220
	v_mul_f32_e32 v146, 0x4b800000, v145
	v_cmp_gt_f32_e32 vcc, s96, v145
	v_fmamk_f32 v147, v147, 0x3a000000, v220
	v_mul_f32_e32 v158, 0x4b800000, v147
	v_cndmask_b32_e32 v145, v145, v146, vcc
	v_rsq_f32_e32 v145, v145
	s_nop 0
	v_mul_f32_e32 v146, 0x45800000, v145
	v_cndmask_b32_e32 v146, v145, v146, vcc
	v_cmp_gt_f32_e32 vcc, s96, v147
	v_pk_mul_f32 v[154:155], v[130:131], v[146:147] op_sel_hi:[1,0]
	v_pk_mul_f32 v[152:153], v[128:129], v[146:147] op_sel_hi:[1,0]
	v_cndmask_b32_e32 v145, v147, v158, vcc
	global_store_dwordx4 v[156:157], v[152:155], off
	v_rsq_f32_e32 v145, v145
	s_nop 0
	v_pk_mul_f32 v[154:155], v[126:127], v[146:147] op_sel_hi:[1,0]
	v_pk_mul_f32 v[152:153], v[124:125], v[146:147] op_sel_hi:[1,0]
	ds_read2_b32 v[146:147], v162 offset0:32 offset1:48
	global_store_dwordx4 v[156:157], v[152:155], off offset:16
	s_nop 1
	v_mul_f32_e32 v152, 0x45800000, v145
	v_cndmask_b32_e32 v158, v145, v152, vcc
	s_waitcnt lgkmcnt(0)
	v_fmamk_f32 v145, v146, 0x3a000000, v220
	v_mul_f32_e32 v146, 0x4b800000, v145
	v_cmp_gt_f32_e32 vcc, s96, v145
	v_pk_mul_f32 v[154:155], v[114:115], v[158:159] op_sel_hi:[1,0]
	v_pk_mul_f32 v[152:153], v[112:113], v[158:159] op_sel_hi:[1,0]
	v_cndmask_b32_e32 v145, v145, v146, vcc
	v_rsq_f32_e32 v145, v145
	global_store_dwordx4 v[156:157], v[152:155], off offset:512
	v_mul_f32_e32 v146, 0x45800000, v145
	s_nop 0
	v_pk_mul_f32 v[154:155], v[110:111], v[158:159] op_sel_hi:[1,0]
	v_pk_mul_f32 v[152:153], v[108:109], v[158:159] op_sel_hi:[1,0]
	v_cndmask_b32_e32 v146, v145, v146, vcc
	v_fmamk_f32 v145, v147, 0x3a000000, v220
	global_store_dwordx4 v[156:157], v[152:155], off offset:528
	v_cmp_gt_f32_e32 vcc, s96, v145
	s_nop 0
	v_pk_mul_f32 v[154:155], v[102:103], v[146:147] op_sel_hi:[1,0]
	v_pk_mul_f32 v[152:153], v[100:101], v[146:147] op_sel_hi:[1,0]
	v_mul_f32_e32 v147, 0x4b800000, v145
	v_cndmask_b32_e32 v145, v145, v147, vcc
	global_store_dwordx4 v[156:157], v[152:155], off offset:1024
	v_rsq_f32_e32 v145, v145
	s_nop 0
	v_pk_mul_f32 v[154:155], v[94:95], v[146:147] op_sel_hi:[1,0]
	v_pk_mul_f32 v[152:153], v[92:93], v[146:147] op_sel_hi:[1,0]
	ds_read2_b32 v[146:147], v162 offset0:128 offset1:144
	global_store_dwordx4 v[156:157], v[152:155], off offset:1040
	s_nop 1
	v_mul_f32_e32 v152, 0x45800000, v145
	v_cndmask_b32_e32 v158, v145, v152, vcc
	s_waitcnt lgkmcnt(0)
	v_fmamk_f32 v145, v146, 0x3a000000, v220
	v_mul_f32_e32 v146, 0x4b800000, v145
	v_cmp_gt_f32_e32 vcc, s96, v145
	v_pk_mul_f32 v[154:155], v[82:83], v[158:159] op_sel_hi:[1,0]
	v_pk_mul_f32 v[152:153], v[80:81], v[158:159] op_sel_hi:[1,0]
	v_cndmask_b32_e32 v145, v145, v146, vcc
	v_rsq_f32_e32 v145, v145
	global_store_dwordx4 v[156:157], v[152:155], off offset:1536
	v_mul_f32_e32 v146, 0x45800000, v145
	v_cndmask_b32_e32 v146, v145, v146, vcc
	v_add_co_u32_e32 v160, vcc, s94, v156
	v_pk_mul_f32 v[154:155], v[78:79], v[158:159] op_sel_hi:[1,0]
	v_pk_mul_f32 v[152:153], v[76:77], v[158:159] op_sel_hi:[1,0]
	v_addc_co_u32_e32 v161, vcc, 0, v157, vcc
	v_fmamk_f32 v145, v147, 0x3a000000, v220
	global_store_dwordx4 v[156:157], v[152:155], off offset:1552
	v_cmp_gt_f32_e32 vcc, s96, v145
	v_lshl_add_u64 v[158:159], v[156:157], 0, s[34:35]
	v_pk_mul_f32 v[154:155], v[66:67], v[146:147] op_sel_hi:[1,0]
	v_pk_mul_f32 v[152:153], v[64:65], v[146:147] op_sel_hi:[1,0]
	v_mul_f32_e32 v147, 0x4b800000, v145
	global_store_dwordx4 v[160:161], v[152:155], off
	v_cndmask_b32_e32 v145, v145, v147, vcc
	v_rsq_f32_e32 v145, v145
	v_pk_mul_f32 v[154:155], v[62:63], v[146:147] op_sel_hi:[1,0]
	v_pk_mul_f32 v[152:153], v[60:61], v[146:147] op_sel_hi:[1,0]
	global_store_dwordx4 v[158:159], v[152:155], off offset:16
	ds_read2_b32 v[158:159], v162 offset0:160 offset1:176
	v_mul_f32_e32 v146, 0x45800000, v145
	v_cndmask_b32_e32 v146, v145, v146, vcc
	v_pk_mul_f32 v[154:155], v[50:51], v[146:147] op_sel_hi:[1,0]
	v_pk_mul_f32 v[152:153], v[48:49], v[146:147] op_sel_hi:[1,0]
	s_waitcnt lgkmcnt(0)
	v_fmamk_f32 v145, v158, 0x3a000000, v220
	v_mul_f32_e32 v147, 0x4b800000, v145
	v_cmp_gt_f32_e32 vcc, s96, v145
	s_mov_b64 s[34:35], 0x1200
	global_store_dwordx4 v[160:161], v[152:155], off offset:512
	v_cndmask_b32_e32 v145, v145, v147, vcc
	v_rsq_f32_e32 v145, v145
	v_pk_mul_f32 v[154:155], v[46:47], v[146:147] op_sel_hi:[1,0]
	v_pk_mul_f32 v[152:153], v[44:45], v[146:147] op_sel_hi:[1,0]
	v_lshl_add_u64 v[162:163], v[156:157], 0, s[34:35]
	v_mul_f32_e32 v146, 0x45800000, v145
	v_cndmask_b32_e32 v146, v145, v146, vcc
	v_fmamk_f32 v145, v159, 0x3a000000, v220
	global_store_dwordx4 v[162:163], v[152:155], off offset:16
	v_cmp_gt_f32_e32 vcc, s96, v145
	s_mov_b64 s[34:35], 0x1400
	v_pk_mul_f32 v[154:155], v[38:39], v[146:147] op_sel_hi:[1,0]
	v_pk_mul_f32 v[152:153], v[36:37], v[146:147] op_sel_hi:[1,0]
	v_mul_f32_e32 v147, 0x4b800000, v145
	v_cndmask_b32_e32 v145, v145, v147, vcc
	v_rsq_f32_e32 v145, v145
	global_store_dwordx4 v[160:161], v[152:155], off offset:1024
	v_lshl_add_u64 v[162:163], v[156:157], 0, s[34:35]
	s_mov_b64 s[34:35], 0x1600
	v_pk_mul_f32 v[154:155], v[30:31], v[146:147] op_sel_hi:[1,0]
	v_pk_mul_f32 v[152:153], v[28:29], v[146:147] op_sel_hi:[1,0]
	v_mul_f32_e32 v146, 0x45800000, v145
	v_cndmask_b32_e32 v146, v145, v146, vcc
	global_store_dwordx4 v[162:163], v[152:155], off offset:16
	v_lshl_add_u64 v[156:157], v[156:157], 0, s[34:35]
	s_nop 0
	v_pk_mul_f32 v[154:155], v[18:19], v[146:147] op_sel_hi:[1,0]
	v_pk_mul_f32 v[152:153], v[16:17], v[146:147] op_sel_hi:[1,0]
	global_store_dwordx4 v[160:161], v[152:155], off offset:1536
	s_nop 1
	v_pk_mul_f32 v[154:155], v[14:15], v[146:147] op_sel_hi:[1,0]
	v_pk_mul_f32 v[152:153], v[12:13], v[146:147] op_sel_hi:[1,0]
	global_store_dwordx4 v[156:157], v[152:155], off offset:16

; #define PG8_STAGE(bufoff, gbase, voff) do { _Pragma("unroll") for (int _i = 0; _i < 2; ++_i) \
;         __builtin_amdgcn_global_load_lds((const unsigned*)((const char*)(gbase) + (voff)[_i]), (LAS unsigned*)(lds + (bufoff) + ldsw + _i * 8192), 16, 0, 0); } while (0)
; #define PG8_WAIT_V(n) asm volatile("s_waitcnt vmcnt(" #n ")" ::: "memory")
; #define PG8_WAIT_L(n) asm volatile("s_waitcnt lgkmcnt(" #n ")" ::: "memory")
; template <class Epi, int LDA, int LDB, int KK>
; __device__ __forceinline__ void gemm_phase(int wv, LAS unsigned char* lds, const Gemm g, const StaticOrder& S, const Epi& E) {
;     ...
;         for (int seg = 0, t = 0; seg < Epi::NSEG; ++seg) {
;           const int tend = Epi::HAS_MID ? (seg == 0 ? Epi::MID1 : (seg == 1 ? Epi::MID2 : nt)) : nt;
;           for (; t < tend; t += 2) {
;             const bool last = (t == nt - 2);
;             const char* a1 = cA + (size_t)(t + 1) * kstep;
;             const char* a2 = last ? nA : cA + (size_t)(t + 2) * kstep; const char* b2 = last ? nB : cB + (size_t)(t + 2) * kstep;
;             const char* a3 = a2 + kstep; const char* b3 = b2 + kstep;
;             PG8_LDB(B0, 0, 0); PG8_SCHED; PG8_LDA(At, 0, 0); PG8_STAGE(PG8_SA(1, 1), a1 + hstepA, voffA);
;             PG8_WAIT_L(8); PG8_BAR; PG8_WAIT_L(0); PG8_MMA(0, 0, At, B0); PG8_BAR; PG8_SCHED;
;             PG8_LDB(B1, 0, 1); PG8_STAGE(PG8_SB(0, 0), b2, voffB);
;             PG8_BAR; PG8_WAIT_L(0); PG8_MMA(0, 1, At, B1); PG8_BAR;
;             PG8_LDA(At, 0, 1); PG8_STAGE(PG8_SA(0, 0), a2, voffA);
;             PG8_BAR; PG8_WAIT_L(0); PG8_MMA(1, 0, At, B0); PG8_BAR; PG8_SCHED;
;             PG8_STAGE(PG8_SB(0, 1), b2 + hstepB, voffB);
;             PG8_WAIT_V(6); PG8_BAR; PG8_MMA(1, 1, At, B1); PG8_BAR;
;             PG8_LDB(B0, 1, 0); PG8_SCHED; PG8_LDA(At, 1, 0); PG8_STAGE(PG8_SA(0, 1), a2 + hstepA, voffA);
;             PG8_WAIT_L(8); PG8_BAR; PG8_WAIT_L(0); PG8_MMA(0, 0, At, B0); PG8_BAR; PG8_SCHED;
;             PG8_LDB(B1, 1, 1); PG8_STAGE(PG8_SB(1, 0), b3, voffB);
;             PG8_BAR; PG8_WAIT_L(0); PG8_MMA(0, 1, At, B1); PG8_BAR;
;             PG8_LDA(At, 1, 1); PG8_STAGE(PG8_SA(1, 0), a3, voffA);
;             PG8_BAR; PG8_WAIT_L(0); PG8_MMA(1, 0, At, B0); PG8_BAR; PG8_SCHED;
;             PG8_STAGE(PG8_SB(1, 1), b3 + hstepB, voffB);
;             PG8_WAIT_V(6); PG8_BAR; PG8_MMA(1, 1, At, B1); PG8_BAR;
.Lmerge_loop:
	s_mov_b32 s26, s22
	s_add_i32 s22, s22, 2
	s_cmp_eq_u32 s26, 30
	s_cselect_b32 s27, s15, s56
	s_cselect_b32 s26, s43, s55
	s_cselect_b32 s25, s13, s47
	s_cselect_b32 s24, s44, s23
	s_waitcnt lgkmcnt(0)
	v_mfma_f32_16x16x32_bf16 v[128:131], v[132:135], v[148:151], v[128:131]
	ds_read_b128 v[180:183], v0 offset:1024
	v_mfma_f32_16x16x32_bf16 v[124:127], v[136:139], v[148:151], v[124:127]
	ds_read_b128 v[184:187], v0 offset:3072
	v_mfma_f32_16x16x32_bf16 v[120:123], v[140:143], v[148:151], v[120:123]
	ds_read_b128 v[188:191], v0 offset:17408
	v_mfma_f32_16x16x32_bf16 v[116:119], v[144:147], v[148:151], v[116:119]
	ds_read_b128 v[192:195], v0 offset:19456
	v_mfma_f32_16x16x32_bf16 v[112:115], v[132:135], v[152:155], v[112:115]
	ds_read_b128 v[164:167], v218 offset:1024
	v_mfma_f32_16x16x32_bf16 v[108:111], v[136:139], v[152:155], v[108:111]
	ds_read_b128 v[168:171], v218 offset:3072
	v_mfma_f32_16x16x32_bf16 v[104:107], v[140:143], v[152:155], v[104:107]
	ds_read_b128 v[172:175], v218 offset:5120
	v_mfma_f32_16x16x32_bf16 v[100:103], v[144:147], v[152:155], v[100:103]
	ds_read_b128 v[176:179], v218 offset:7168
	v_mfma_f32_16x16x32_bf16 v[96:99], v[132:135], v[156:159], v[96:99]
	v_mfma_f32_16x16x32_bf16 v[92:95], v[136:139], v[156:159], v[92:95]
	v_mfma_f32_16x16x32_bf16 v[88:91], v[140:143], v[156:159], v[88:91]
	v_mfma_f32_16x16x32_bf16 v[84:87], v[144:147], v[156:159], v[84:87]
	v_mfma_f32_16x16x32_bf16 v[80:83], v[132:135], v[160:163], v[80:83]
	v_mfma_f32_16x16x32_bf16 v[76:79], v[136:139], v[160:163], v[76:79]
	v_mfma_f32_16x16x32_bf16 v[72:75], v[140:143], v[160:163], v[72:75]
	v_mfma_f32_16x16x32_bf16 v[68:71], v[144:147], v[160:163], v[68:71]
	s_waitcnt vmcnt(8) lgkmcnt(0)
	s_barrier
	v_mfma_f32_16x16x32_bf16 v[128:131], v[180:183], v[164:167], v[128:131]
	ds_read_b128 v[148:151], v218 offset:16384
	v_mfma_f32_16x16x32_bf16 v[124:127], v[184:187], v[164:167], v[124:127]
	ds_read_b128 v[152:155], v218 offset:18432
	v_mfma_f32_16x16x32_bf16 v[120:123], v[188:191], v[164:167], v[120:123]
	ds_read_b128 v[156:159], v218 offset:20480
	v_mfma_f32_16x16x32_bf16 v[116:119], v[192:195], v[164:167], v[116:119]
	ds_read_b128 v[160:163], v218 offset:22528
	v_mfma_f32_16x16x32_bf16 v[112:115], v[180:183], v[168:171], v[112:115]
	s_add_i32 m0, s36, 0x10000
	v_mfma_f32_16x16x32_bf16 v[108:111], v[184:187], v[168:171], v[108:111]
	global_load_lds_dwordx4 v206, s[24:25]
	v_mfma_f32_16x16x32_bf16 v[104:107], v[188:191], v[168:171], v[104:107]
	v_mfma_f32_16x16x32_bf16 v[100:103], v[192:195], v[168:171], v[100:103]
	s_add_i32 m0, s36, 0x12000
	v_mfma_f32_16x16x32_bf16 v[96:99], v[180:183], v[172:175], v[96:99]
	global_load_lds_dwordx4 v202, s[24:25]
	v_mfma_f32_16x16x32_bf16 v[92:95], v[184:187], v[172:175], v[92:95]
	v_mfma_f32_16x16x32_bf16 v[88:91], v[188:191], v[172:175], v[88:91]
	s_mov_b32 m0, s36
	v_mfma_f32_16x16x32_bf16 v[84:87], v[192:195], v[172:175], v[84:87]
	global_load_lds_dwordx4 v208, s[26:27]
	v_mfma_f32_16x16x32_bf16 v[80:83], v[180:183], v[176:179], v[80:83]
	v_mfma_f32_16x16x32_bf16 v[76:79], v[184:187], v[176:179], v[76:79]
	v_mfma_f32_16x16x32_bf16 v[72:75], v[188:191], v[176:179], v[72:75]
	v_mfma_f32_16x16x32_bf16 v[68:71], v[192:195], v[176:179], v[68:71]
	s_waitcnt lgkmcnt(0)
	v_mfma_f32_16x16x32_bf16 v[64:67], v[132:135], v[148:151], v[64:67]
	ds_read_b128 v[164:167], v218 offset:17408
	v_mfma_f32_16x16x32_bf16 v[60:63], v[136:139], v[148:151], v[60:63]
	ds_read_b128 v[168:171], v218 offset:19456
	v_mfma_f32_16x16x32_bf16 v[56:59], v[140:143], v[148:151], v[56:59]
	ds_read_b128 v[172:175], v218 offset:21504
	v_mfma_f32_16x16x32_bf16 v[52:55], v[144:147], v[148:151], v[52:55]
	ds_read_b128 v[176:179], v218 offset:23552
	v_mfma_f32_16x16x32_bf16 v[48:51], v[132:135], v[152:155], v[48:51]
	s_add_i32 m0, s36, 0x2000
	v_mfma_f32_16x16x32_bf16 v[44:47], v[136:139], v[152:155], v[44:47]
	global_load_lds_dwordx4 v204, s[26:27]
	v_mfma_f32_16x16x32_bf16 v[40:43], v[140:143], v[152:155], v[40:43]
	v_mfma_f32_16x16x32_bf16 v[36:39], v[144:147], v[152:155], v[36:39]
	s_add_u32 s98, s24, 0x80000
	s_addc_u32 s99, s25, 0
	s_add_i32 m0, s36, 0x14000
	v_mfma_f32_16x16x32_bf16 v[32:35], v[132:135], v[156:159], v[32:35]
	global_load_lds_dwordx4 v206, s[98:99]
	v_mfma_f32_16x16x32_bf16 v[28:31], v[136:139], v[156:159], v[28:31]
	v_mfma_f32_16x16x32_bf16 v[24:27], v[140:143], v[156:159], v[24:27]
	s_add_i32 m0, s36, 0x16000
	v_mfma_f32_16x16x32_bf16 v[20:23], v[144:147], v[156:159], v[20:23]
	global_load_lds_dwordx4 v202, s[98:99]
	v_mfma_f32_16x16x32_bf16 v[16:19], v[132:135], v[160:163], v[16:19]
	v_mfma_f32_16x16x32_bf16 v[12:15], v[136:139], v[160:163], v[12:15]
	v_mfma_f32_16x16x32_bf16 v[8:11], v[140:143], v[160:163], v[8:11]
	v_mfma_f32_16x16x32_bf16 v[4:7], v[144:147], v[160:163], v[4:7]
	s_waitcnt vmcnt(8) lgkmcnt(0)
	s_barrier
; #define PG8_STAGE(bufoff, gbase, voff) do { _Pragma("unroll") for (int _i = 0; _i < 2; ++_i) \
;         __builtin_amdgcn_global_load_lds((const unsigned*)((const char*)(gbase) + (voff)[_i]), (LAS unsigned*)(lds + (bufoff) + ldsw + _i * 8192), 16, 0, 0); } while (0)
; #define PG8_LDA(dst, b, h) do { _Pragma("unroll") for (int m = 0; m < 4; ++m) _Pragma("unroll") for (int k = 0; k < 2; ++k) dst[m][k] = *(const LAS bf16x8*)(lds + PG8_SA(b, h) + aoff + m * 2048 + k * 1024); } while (0)
; #define PG8_LDB(dst, b, h) do { _Pragma("unroll") for (int n = 0; n < 2; ++n) _Pragma("unroll") for (int k = 0; k < 2; ++k) dst[n][k] = *(const LAS bf16x8*)(lds + PG8_SB(b, h) + boff + n * 2048 + k * 1024); } while (0)
; #define PG8_WAIT_V(n) asm volatile("s_waitcnt vmcnt(" #n ")" ::: "memory")
; #define PG8_WAIT_L(n) asm volatile("s_waitcnt lgkmcnt(" #n ")" ::: "memory")
; #define PG8_BAR __builtin_amdgcn_s_barrier()
; #define PG8_SCHED __builtin_amdgcn_sched_barrier(0)
; template <class Epi, int LDA, int LDB, int KK>
; __device__ __forceinline__ void gemm_phase(int wv, LAS unsigned char* lds, const Gemm g, const StaticOrder& S, const Epi& E) {
;     ...
;             PG8_LDB(B0, 0, 0); PG8_SCHED; PG8_LDA(At, 0, 0); PG8_STAGE(PG8_SA(1, 1), a1 + hstepA, voffA);
;             PG8_WAIT_L(8); PG8_BAR; PG8_WAIT_L(0); PG8_MMA(0, 0, At, B0); PG8_BAR; PG8_SCHED;
;             PG8_LDB(B1, 0, 1); PG8_STAGE(PG8_SB(0, 0), b2, voffB);
;             PG8_BAR; PG8_WAIT_L(0); PG8_MMA(0, 1, At, B1); PG8_BAR;
;             PG8_LDA(At, 0, 1); PG8_STAGE(PG8_SA(0, 0), a2, voffA);
;             PG8_BAR; PG8_WAIT_L(0); PG8_MMA(1, 0, At, B0); PG8_BAR; PG8_SCHED;
;             PG8_STAGE(PG8_SB(0, 1), b2 + hstepB, voffB);
;             PG8_WAIT_V(6); PG8_BAR; PG8_MMA(1, 1, At, B1); PG8_BAR;
;             PG8_LDB(B0, 1, 0); PG8_SCHED; PG8_LDA(At, 1, 0); PG8_STAGE(PG8_SA(0, 1), a2 + hstepA, voffA);
;             PG8_WAIT_L(8); PG8_BAR; PG8_WAIT_L(0); PG8_MMA(0, 0, At, B0); PG8_BAR; PG8_SCHED;
;             PG8_LDB(B1, 1, 1); PG8_STAGE(PG8_SB(1, 0), b3, voffB);
;             PG8_BAR; PG8_WAIT_L(0); PG8_MMA(0, 1, At, B1); PG8_BAR;
;             PG8_LDA(At, 1, 1); PG8_STAGE(PG8_SA(1, 0), a3, voffA);
;             PG8_BAR; PG8_WAIT_L(0); PG8_MMA(1, 0, At, B0); PG8_BAR; PG8_SCHED;
;             PG8_STAGE(PG8_SB(1, 1), b3 + hstepB, voffB);
;             PG8_WAIT_V(6); PG8_BAR; PG8_MMA(1, 1, At, B1); PG8_BAR;
	v_mfma_f32_16x16x32_bf16 v[64:67], v[180:183], v[164:167], v[64:67]
	ds_read_b128 v[132:135], v0 offset:32768
	v_mfma_f32_16x16x32_bf16 v[60:63], v[184:187], v[164:167], v[60:63]
	ds_read_b128 v[136:139], v0 offset:34816
	v_mfma_f32_16x16x32_bf16 v[56:59], v[188:191], v[164:167], v[56:59]
	ds_read_b128 v[140:143], v0 offset:49152
	v_mfma_f32_16x16x32_bf16 v[52:55], v[192:195], v[164:167], v[52:55]
	ds_read_b128 v[144:147], v0 offset:51200
	v_mfma_f32_16x16x32_bf16 v[48:51], v[180:183], v[168:171], v[48:51]
	ds_read_b128 v[148:151], v218 offset:32768
	v_mfma_f32_16x16x32_bf16 v[44:47], v[184:187], v[168:171], v[44:47]
	ds_read_b128 v[152:155], v218 offset:34816
	v_mfma_f32_16x16x32_bf16 v[40:43], v[188:191], v[168:171], v[40:43]
	ds_read_b128 v[156:159], v218 offset:36864
	v_mfma_f32_16x16x32_bf16 v[36:39], v[192:195], v[168:171], v[36:39]
	ds_read_b128 v[160:163], v218 offset:38912
	v_mfma_f32_16x16x32_bf16 v[32:35], v[180:183], v[172:175], v[32:35]
	s_add_u32 s98, s26, 0x80000
	s_addc_u32 s99, s27, 0
	s_add_i32 m0, s36, 0x4000
	v_mfma_f32_16x16x32_bf16 v[28:31], v[184:187], v[172:175], v[28:31]
	global_load_lds_dwordx4 v208, s[98:99]
	v_mfma_f32_16x16x32_bf16 v[24:27], v[188:191], v[172:175], v[24:27]
	v_mfma_f32_16x16x32_bf16 v[20:23], v[192:195], v[172:175], v[20:23]
	s_add_i32 m0, s36, 0x6000
	v_mfma_f32_16x16x32_bf16 v[16:19], v[180:183], v[176:179], v[16:19]
	global_load_lds_dwordx4 v204, s[98:99]
	v_mfma_f32_16x16x32_bf16 v[12:15], v[184:187], v[176:179], v[12:15]
	v_mfma_f32_16x16x32_bf16 v[8:11], v[188:191], v[176:179], v[8:11]
	v_mfma_f32_16x16x32_bf16 v[4:7], v[192:195], v[176:179], v[4:7]
	s_add_u32 s24, s24, 0x80
	s_addc_u32 s25, s25, 0
	s_add_u32 s26, s26, 0x80
	s_addc_u32 s27, s27, 0
	s_waitcnt lgkmcnt(0)
	v_mfma_f32_16x16x32_bf16 v[128:131], v[132:135], v[148:151], v[128:131]
	ds_read_b128 v[180:183], v0 offset:33792
	v_mfma_f32_16x16x32_bf16 v[124:127], v[136:139], v[148:151], v[124:127]
	ds_read_b128 v[184:187], v0 offset:35840
	v_mfma_f32_16x16x32_bf16 v[120:123], v[140:143], v[148:151], v[120:123]
	ds_read_b128 v[188:191], v0 offset:50176
	v_mfma_f32_16x16x32_bf16 v[116:119], v[144:147], v[148:151], v[116:119]
	ds_read_b128 v[192:195], v0 offset:52224
	v_mfma_f32_16x16x32_bf16 v[112:115], v[132:135], v[152:155], v[112:115]
	ds_read_b128 v[164:167], v218 offset:33792
	v_mfma_f32_16x16x32_bf16 v[108:111], v[136:139], v[152:155], v[108:111]
	ds_read_b128 v[168:171], v218 offset:35840
	v_mfma_f32_16x16x32_bf16 v[104:107], v[140:143], v[152:155], v[104:107]
	ds_read_b128 v[172:175], v218 offset:37888
	v_mfma_f32_16x16x32_bf16 v[100:103], v[144:147], v[152:155], v[100:103]
	ds_read_b128 v[176:179], v218 offset:39936
	v_mfma_f32_16x16x32_bf16 v[96:99], v[132:135], v[156:159], v[96:99]
	v_mfma_f32_16x16x32_bf16 v[92:95], v[136:139], v[156:159], v[92:95]
	v_mfma_f32_16x16x32_bf16 v[88:91], v[140:143], v[156:159], v[88:91]
	v_mfma_f32_16x16x32_bf16 v[84:87], v[144:147], v[156:159], v[84:87]
	v_mfma_f32_16x16x32_bf16 v[80:83], v[132:135], v[160:163], v[80:83]
	v_mfma_f32_16x16x32_bf16 v[76:79], v[136:139], v[160:163], v[76:79]
	v_mfma_f32_16x16x32_bf16 v[72:75], v[140:143], v[160:163], v[72:75]
	v_mfma_f32_16x16x32_bf16 v[68:71], v[144:147], v[160:163], v[68:71]
	s_waitcnt vmcnt(8) lgkmcnt(0)
	s_barrier
; #define PG8_STAGE(bufoff, gbase, voff) do { _Pragma("unroll") for (int _i = 0; _i < 2; ++_i) \
;         __builtin_amdgcn_global_load_lds((const unsigned*)((const char*)(gbase) + (voff)[_i]), (LAS unsigned*)(lds + (bufoff) + ldsw + _i * 8192), 16, 0, 0); } while (0)
; #define PG8_LDA(dst, b, h) do { _Pragma("unroll") for (int m = 0; m < 4; ++m) _Pragma("unroll") for (int k = 0; k < 2; ++k) dst[m][k] = *(const LAS bf16x8*)(lds + PG8_SA(b, h) + aoff + m * 2048 + k * 1024); } while (0)
; #define PG8_LDB(dst, b, h) do { _Pragma("unroll") for (int n = 0; n < 2; ++n) _Pragma("unroll") for (int k = 0; k < 2; ++k) dst[n][k] = *(const LAS bf16x8*)(lds + PG8_SB(b, h) + boff + n * 2048 + k * 1024); } while (0)
; #define PG8_MMA(ai, bj, At, Bt) do { __builtin_amdgcn_s_setprio(1); _Pragma("unroll") for (int m = 0; m < 4; ++m) _Pragma("unroll") for (int n = 0; n < 2; ++n) _Pragma("unroll") for (int k = 0; k < 2; ++k) \
;         acc[ai][bj][m][n] = __builtin_amdgcn_mfma_f32_16x16x32_bf16(Bt[n][k], At[m][k], acc[ai][bj][m][n], 0, 0, 0); __builtin_amdgcn_s_setprio(0); } while (0)
; #define PG8_WAIT_V(n) asm volatile("s_waitcnt vmcnt(" #n ")" ::: "memory")
; #define PG8_WAIT_L(n) asm volatile("s_waitcnt lgkmcnt(" #n ")" ::: "memory")
; #define PG8_BAR __builtin_amdgcn_s_barrier()
; #define PG8_SCHED __builtin_amdgcn_sched_barrier(0)
; template <class Epi, int LDA, int LDB, int KK>
; __device__ __forceinline__ void gemm_phase(int wv, LAS unsigned char* lds, const Gemm g, const StaticOrder& S, const Epi& E) {
;     ...
;             PG8_LDB(B0, 1, 0); PG8_SCHED; PG8_LDA(At, 1, 0); PG8_STAGE(PG8_SA(0, 1), a2 + hstepA, voffA);
;             PG8_WAIT_L(8); PG8_BAR; PG8_WAIT_L(0); PG8_MMA(0, 0, At, B0); PG8_BAR; PG8_SCHED;
;             PG8_LDB(B1, 1, 1); PG8_STAGE(PG8_SB(1, 0), b3, voffB);
;             PG8_BAR; PG8_WAIT_L(0); PG8_MMA(0, 1, At, B1); PG8_BAR;
;             PG8_LDA(At, 1, 1); PG8_STAGE(PG8_SA(1, 0), a3, voffA);
;             PG8_BAR; PG8_WAIT_L(0); PG8_MMA(1, 0, At, B0); PG8_BAR; PG8_SCHED;
;             PG8_STAGE(PG8_SB(1, 1), b3 + hstepB, voffB);
;             PG8_WAIT_V(6); PG8_BAR; PG8_MMA(1, 1, At, B1); PG8_BAR;
;           }
;           if constexpr (Epi::HAS_MID) { if (seg < Epi::NSEG - 1) E.mid(acc, cur, seg, wr, wc, fr, fq); }
	v_mfma_f32_16x16x32_bf16 v[128:131], v[180:183], v[164:167], v[128:131]
	ds_read_b128 v[148:151], v218 offset:49152
	v_mfma_f32_16x16x32_bf16 v[124:127], v[184:187], v[164:167], v[124:127]
	ds_read_b128 v[152:155], v218 offset:51200
	v_mfma_f32_16x16x32_bf16 v[120:123], v[188:191], v[164:167], v[120:123]
	ds_read_b128 v[156:159], v218 offset:53248
	v_mfma_f32_16x16x32_bf16 v[116:119], v[192:195], v[164:167], v[116:119]
	ds_read_b128 v[160:163], v218 offset:55296
	v_mfma_f32_16x16x32_bf16 v[112:115], v[180:183], v[168:171], v[112:115]
	s_add_i32 m0, s36, 0x18000
	v_mfma_f32_16x16x32_bf16 v[108:111], v[184:187], v[168:171], v[108:111]
	global_load_lds_dwordx4 v206, s[24:25]
	v_mfma_f32_16x16x32_bf16 v[104:107], v[188:191], v[168:171], v[104:107]
	v_mfma_f32_16x16x32_bf16 v[100:103], v[192:195], v[168:171], v[100:103]
	s_add_i32 m0, s36, 0x1a000
	v_mfma_f32_16x16x32_bf16 v[96:99], v[180:183], v[172:175], v[96:99]
	global_load_lds_dwordx4 v202, s[24:25]
	v_mfma_f32_16x16x32_bf16 v[92:95], v[184:187], v[172:175], v[92:95]
	v_mfma_f32_16x16x32_bf16 v[88:91], v[188:191], v[172:175], v[88:91]
	s_add_i32 m0, s36, 0x8000
	v_mfma_f32_16x16x32_bf16 v[84:87], v[192:195], v[172:175], v[84:87]
	global_load_lds_dwordx4 v208, s[26:27]
	v_mfma_f32_16x16x32_bf16 v[80:83], v[180:183], v[176:179], v[80:83]
	v_mfma_f32_16x16x32_bf16 v[76:79], v[184:187], v[176:179], v[76:79]
	v_mfma_f32_16x16x32_bf16 v[72:75], v[188:191], v[176:179], v[72:75]
	v_mfma_f32_16x16x32_bf16 v[68:71], v[192:195], v[176:179], v[68:71]
	s_waitcnt lgkmcnt(0)
	v_mfma_f32_16x16x32_bf16 v[64:67], v[132:135], v[148:151], v[64:67]
	ds_read_b128 v[164:167], v218 offset:50176
	v_mfma_f32_16x16x32_bf16 v[60:63], v[136:139], v[148:151], v[60:63]
	ds_read_b128 v[168:171], v218 offset:52224
	v_mfma_f32_16x16x32_bf16 v[56:59], v[140:143], v[148:151], v[56:59]
	ds_read_b128 v[172:175], v218 offset:54272
	v_mfma_f32_16x16x32_bf16 v[52:55], v[144:147], v[148:151], v[52:55]
	ds_read_b128 v[176:179], v218 offset:56320
	v_mfma_f32_16x16x32_bf16 v[48:51], v[132:135], v[152:155], v[48:51]
	s_add_i32 m0, s36, 0xa000
	v_mfma_f32_16x16x32_bf16 v[44:47], v[136:139], v[152:155], v[44:47]
	global_load_lds_dwordx4 v204, s[26:27]
	v_mfma_f32_16x16x32_bf16 v[40:43], v[140:143], v[152:155], v[40:43]
	v_mfma_f32_16x16x32_bf16 v[36:39], v[144:147], v[152:155], v[36:39]
	s_add_u32 s98, s24, 0x80000
	s_addc_u32 s99, s25, 0
	s_add_i32 m0, s36, 0x1c000
	v_mfma_f32_16x16x32_bf16 v[32:35], v[132:135], v[156:159], v[32:35]
	global_load_lds_dwordx4 v206, s[98:99]
	v_mfma_f32_16x16x32_bf16 v[28:31], v[136:139], v[156:159], v[28:31]
	v_mfma_f32_16x16x32_bf16 v[24:27], v[140:143], v[156:159], v[24:27]
	s_add_i32 m0, s36, 0x1e000
	v_mfma_f32_16x16x32_bf16 v[20:23], v[144:147], v[156:159], v[20:23]
	global_load_lds_dwordx4 v202, s[98:99]
	v_mfma_f32_16x16x32_bf16 v[16:19], v[132:135], v[160:163], v[16:19]
	v_mfma_f32_16x16x32_bf16 v[12:15], v[136:139], v[160:163], v[12:15]
	v_mfma_f32_16x16x32_bf16 v[8:11], v[140:143], v[160:163], v[8:11]
	v_mfma_f32_16x16x32_bf16 v[4:7], v[144:147], v[160:163], v[4:7]
	s_waitcnt vmcnt(8) lgkmcnt(0)
	s_barrier
	v_mfma_f32_16x16x32_bf16 v[64:67], v[180:183], v[164:167], v[64:67]
	ds_read_b128 v[132:135], v0 offset:0
	v_mfma_f32_16x16x32_bf16 v[60:63], v[184:187], v[164:167], v[60:63]
	ds_read_b128 v[136:139], v0 offset:2048
	v_mfma_f32_16x16x32_bf16 v[56:59], v[188:191], v[164:167], v[56:59]
	ds_read_b128 v[140:143], v0 offset:16384
	v_mfma_f32_16x16x32_bf16 v[52:55], v[192:195], v[164:167], v[52:55]
	ds_read_b128 v[144:147], v0 offset:18432
	v_mfma_f32_16x16x32_bf16 v[48:51], v[180:183], v[168:171], v[48:51]
	ds_read_b128 v[148:151], v218 offset:0
	v_mfma_f32_16x16x32_bf16 v[44:47], v[184:187], v[168:171], v[44:47]
	ds_read_b128 v[152:155], v218 offset:2048
	v_mfma_f32_16x16x32_bf16 v[40:43], v[188:191], v[168:171], v[40:43]
	ds_read_b128 v[156:159], v218 offset:4096
	v_mfma_f32_16x16x32_bf16 v[36:39], v[192:195], v[168:171], v[36:39]
	ds_read_b128 v[160:163], v218 offset:6144
	v_mfma_f32_16x16x32_bf16 v[32:35], v[180:183], v[172:175], v[32:35]
	s_add_u32 s98, s26, 0x80000
	s_addc_u32 s99, s27, 0
	s_add_i32 m0, s36, 0xc000
	v_mfma_f32_16x16x32_bf16 v[28:31], v[184:187], v[172:175], v[28:31]
	global_load_lds_dwordx4 v208, s[98:99]
	v_mfma_f32_16x16x32_bf16 v[24:27], v[188:191], v[172:175], v[24:27]
	v_mfma_f32_16x16x32_bf16 v[20:23], v[192:195], v[172:175], v[20:23]
	s_add_i32 m0, s36, 0xe000
	v_mfma_f32_16x16x32_bf16 v[16:19], v[180:183], v[176:179], v[16:19]
	global_load_lds_dwordx4 v204, s[98:99]
	v_mfma_f32_16x16x32_bf16 v[12:15], v[184:187], v[176:179], v[12:15]
	v_mfma_f32_16x16x32_bf16 v[8:11], v[188:191], v[176:179], v[8:11]
	v_mfma_f32_16x16x32_bf16 v[4:7], v[192:195], v[176:179], v[4:7]
	s_add_u32 s23, s23, 0x100
	s_addc_u32 s47, s47, 0
	s_add_u32 s55, s55, 0x100
	s_addc_u32 s56, s56, 0
	s_cmp_lt_i32 s22, s46
	s_cbranch_scc1 .Lmerge_loop
	s_waitcnt lgkmcnt(0)

; #define PG8_STAGE(bufoff, gbase, voff) do { _Pragma("unroll") for (int _i = 0; _i < 2; ++_i) \
;         __builtin_amdgcn_global_load_lds((const unsigned*)((const char*)(gbase) + (voff)[_i]), (LAS unsigned*)(lds + (bufoff) + ldsw + _i * 8192), 16, 0, 0); } while (0)
; #define PG8_LDA(dst, b, h) do { _Pragma("unroll") for (int m = 0; m < 4; ++m) _Pragma("unroll") for (int k = 0; k < 2; ++k) dst[m][k] = *(const LAS bf16x8*)(lds + PG8_SA(b, h) + aoff + m * 2048 + k * 1024); } while (0)
; #define PG8_WAIT_V(n) asm volatile("s_waitcnt vmcnt(" #n ")" ::: "memory")
; #define PG8_BAR __builtin_amdgcn_s_barrier()
; template <class Epi, int LDA, int LDB, int KK>
; __device__ __forceinline__ void gemm_phase(int wv, LAS unsigned char* lds, const Gemm g, const StaticOrder& S, const Epi& E) {
;     ...
;           for (; t < tend; t += 2) {
;             const bool last = (t == nt - 2);
;             const char* a1 = cA + (size_t)(t + 1) * kstep;
;             const char* a2 = last ? nA : cA + (size_t)(t + 2) * kstep; const char* b2 = last ? nB : cB + (size_t)(t + 2) * kstep;
;             const char* a3 = a2 + kstep; const char* b3 = b2 + kstep;
;             PG8_LDB(B0, 0, 0); PG8_SCHED; PG8_LDA(At, 0, 0); PG8_STAGE(PG8_SA(1, 1), a1 + hstepA, voffA);
;             PG8_WAIT_L(8); PG8_BAR; PG8_WAIT_L(0); PG8_MMA(0, 0, At, B0); PG8_BAR; PG8_SCHED;
;             PG8_LDB(B1, 0, 1); PG8_STAGE(PG8_SB(0, 0), b2, voffB);
;             PG8_BAR; PG8_WAIT_L(0); PG8_MMA(0, 1, At, B1); PG8_BAR;
;             PG8_LDA(At, 0, 1); PG8_STAGE(PG8_SA(0, 0), a2, voffA);
;             PG8_BAR; PG8_WAIT_L(0); PG8_MMA(1, 0, At, B0); PG8_BAR; PG8_SCHED;
;             PG8_STAGE(PG8_SB(0, 1), b2 + hstepB, voffB);
;             PG8_WAIT_V(6); PG8_BAR; PG8_MMA(1, 1, At, B1); PG8_BAR;
;             PG8_LDB(B0, 1, 0); PG8_SCHED; PG8_LDA(At, 1, 0); PG8_STAGE(PG8_SA(0, 1), a2 + hstepA, voffA);
;             PG8_WAIT_L(8); PG8_BAR; PG8_WAIT_L(0); PG8_MMA(0, 0, At, B0); PG8_BAR; PG8_SCHED;
;             PG8_LDB(B1, 1, 1); PG8_STAGE(PG8_SB(1, 0), b3, voffB);
;             PG8_BAR; PG8_WAIT_L(0); PG8_MMA(0, 1, At, B1); PG8_BAR;
;             PG8_LDA(At, 1, 1); PG8_STAGE(PG8_SA(1, 0), a3, voffA);
;             PG8_BAR; PG8_WAIT_L(0); PG8_MMA(1, 0, At, B0); PG8_BAR; PG8_SCHED;
;             PG8_STAGE(PG8_SB(1, 1), b3 + hstepB, voffB);
;             PG8_WAIT_V(6); PG8_BAR; PG8_MMA(1, 1, At, B1); PG8_BAR;
.Lout_loop:
	s_add_u32 s26, s24, 0xfff80080
	s_addc_u32 s27, s25, -1
	s_cmp_eq_u32 s69, 28
	s_cselect_b32 s29, s17, s27
	s_cselect_b32 s28, s47, s26
	s_cselect_b32 s27, s15, s68
	s_cselect_b32 s26, s55, s56
	s_waitcnt lgkmcnt(0)
	v_mfma_f32_16x16x32_bf16 v[128:131], v[132:135], v[148:151], v[128:131]
	ds_read_b128 v[202:205], v180 offset:1024
	v_mfma_f32_16x16x32_bf16 v[124:127], v[136:139], v[148:151], v[124:127]
	ds_read_b128 v[206:209], v180 offset:3072
	v_mfma_f32_16x16x32_bf16 v[120:123], v[140:143], v[148:151], v[120:123]
	ds_read_b128 v[210:213], v180 offset:17408
	v_mfma_f32_16x16x32_bf16 v[116:119], v[144:147], v[148:151], v[116:119]
	ds_read_b128 v[214:217], v180 offset:19456
	v_mfma_f32_16x16x32_bf16 v[112:115], v[132:135], v[152:155], v[112:115]
	ds_read_b128 v[164:167], v234 offset:1024
	v_mfma_f32_16x16x32_bf16 v[108:111], v[136:139], v[152:155], v[108:111]
	ds_read_b128 v[168:171], v234 offset:3072
	v_mfma_f32_16x16x32_bf16 v[104:107], v[140:143], v[152:155], v[104:107]
	ds_read_b128 v[172:175], v234 offset:5120
	v_mfma_f32_16x16x32_bf16 v[100:103], v[144:147], v[152:155], v[100:103]
	ds_read_b128 v[176:179], v234 offset:7168
	v_mfma_f32_16x16x32_bf16 v[96:99], v[132:135], v[156:159], v[96:99]
	v_mfma_f32_16x16x32_bf16 v[92:95], v[136:139], v[156:159], v[92:95]
	v_mfma_f32_16x16x32_bf16 v[88:91], v[140:143], v[156:159], v[88:91]
	v_mfma_f32_16x16x32_bf16 v[84:87], v[144:147], v[156:159], v[84:87]
	v_mfma_f32_16x16x32_bf16 v[80:83], v[132:135], v[160:163], v[80:83]
	v_mfma_f32_16x16x32_bf16 v[76:79], v[136:139], v[160:163], v[76:79]
	v_mfma_f32_16x16x32_bf16 v[72:75], v[140:143], v[160:163], v[72:75]
	v_mfma_f32_16x16x32_bf16 v[68:71], v[144:147], v[160:163], v[68:71]
	s_waitcnt vmcnt(8) lgkmcnt(0)
	s_barrier
	v_mfma_f32_16x16x32_bf16 v[128:131], v[202:205], v[164:167], v[128:131]
	ds_read_b128 v[148:151], v234 offset:16384
	v_mfma_f32_16x16x32_bf16 v[124:127], v[206:209], v[164:167], v[124:127]
	ds_read_b128 v[152:155], v234 offset:18432
	v_mfma_f32_16x16x32_bf16 v[120:123], v[210:213], v[164:167], v[120:123]
	ds_read_b128 v[156:159], v234 offset:20480
	v_mfma_f32_16x16x32_bf16 v[116:119], v[214:217], v[164:167], v[116:119]
	ds_read_b128 v[160:163], v234 offset:22528
	v_mfma_f32_16x16x32_bf16 v[112:115], v[202:205], v[168:171], v[112:115]
	s_add_i32 m0, s40, 0x10000
	v_mfma_f32_16x16x32_bf16 v[108:111], v[206:209], v[168:171], v[108:111]
	global_load_lds_dwordx4 v2, s[26:27]
	v_mfma_f32_16x16x32_bf16 v[104:107], v[210:213], v[168:171], v[104:107]
	v_mfma_f32_16x16x32_bf16 v[100:103], v[214:217], v[168:171], v[100:103]
	s_add_i32 m0, s40, 0x12000
	v_mfma_f32_16x16x32_bf16 v[96:99], v[202:205], v[172:175], v[96:99]
	global_load_lds_dwordx4 v0, s[26:27]
	v_mfma_f32_16x16x32_bf16 v[92:95], v[206:209], v[172:175], v[92:95]
	v_mfma_f32_16x16x32_bf16 v[88:91], v[210:213], v[172:175], v[88:91]
	s_mov_b32 m0, s40
	v_mfma_f32_16x16x32_bf16 v[84:87], v[214:217], v[172:175], v[84:87]
	global_load_lds_dwordx4 v190, s[28:29]
	v_mfma_f32_16x16x32_bf16 v[80:83], v[202:205], v[176:179], v[80:83]
	v_mfma_f32_16x16x32_bf16 v[76:79], v[206:209], v[176:179], v[76:79]
	v_mfma_f32_16x16x32_bf16 v[72:75], v[210:213], v[176:179], v[72:75]
	v_mfma_f32_16x16x32_bf16 v[68:71], v[214:217], v[176:179], v[68:71]
	s_waitcnt lgkmcnt(0)
	v_mfma_f32_16x16x32_bf16 v[64:67], v[132:135], v[148:151], v[64:67]
	ds_read_b128 v[164:167], v234 offset:17408
	v_mfma_f32_16x16x32_bf16 v[60:63], v[136:139], v[148:151], v[60:63]
	ds_read_b128 v[168:171], v234 offset:19456
	v_mfma_f32_16x16x32_bf16 v[56:59], v[140:143], v[148:151], v[56:59]
	ds_read_b128 v[172:175], v234 offset:21504
	v_mfma_f32_16x16x32_bf16 v[52:55], v[144:147], v[148:151], v[52:55]
	ds_read_b128 v[176:179], v234 offset:23552
	v_mfma_f32_16x16x32_bf16 v[48:51], v[132:135], v[152:155], v[48:51]
	s_add_i32 m0, s40, 0x2000
	v_mfma_f32_16x16x32_bf16 v[44:47], v[136:139], v[152:155], v[44:47]
	global_load_lds_dwordx4 v188, s[28:29]
	v_mfma_f32_16x16x32_bf16 v[40:43], v[140:143], v[152:155], v[40:43]
	v_mfma_f32_16x16x32_bf16 v[36:39], v[144:147], v[152:155], v[36:39]
	s_add_u32 s98, s26, 0x80000
	s_addc_u32 s99, s27, 0
	s_add_i32 m0, s40, 0x14000
	v_mfma_f32_16x16x32_bf16 v[32:35], v[132:135], v[156:159], v[32:35]
	global_load_lds_dwordx4 v2, s[98:99]
	v_mfma_f32_16x16x32_bf16 v[28:31], v[136:139], v[156:159], v[28:31]
	v_mfma_f32_16x16x32_bf16 v[24:27], v[140:143], v[156:159], v[24:27]
	s_add_i32 m0, s40, 0x16000
	v_mfma_f32_16x16x32_bf16 v[20:23], v[144:147], v[156:159], v[20:23]
	global_load_lds_dwordx4 v0, s[98:99]
	v_mfma_f32_16x16x32_bf16 v[16:19], v[132:135], v[160:163], v[16:19]
	v_mfma_f32_16x16x32_bf16 v[12:15], v[136:139], v[160:163], v[12:15]
	v_mfma_f32_16x16x32_bf16 v[8:11], v[140:143], v[160:163], v[8:11]
	v_mfma_f32_16x16x32_bf16 v[4:7], v[144:147], v[160:163], v[4:7]
	s_waitcnt vmcnt(8) lgkmcnt(0)
	s_barrier
; #define PG8_STAGE(bufoff, gbase, voff) do { _Pragma("unroll") for (int _i = 0; _i < 2; ++_i) \
;         __builtin_amdgcn_global_load_lds((const unsigned*)((const char*)(gbase) + (voff)[_i]), (LAS unsigned*)(lds + (bufoff) + ldsw + _i * 8192), 16, 0, 0); } while (0)
; #define PG8_LDA(dst, b, h) do { _Pragma("unroll") for (int m = 0; m < 4; ++m) _Pragma("unroll") for (int k = 0; k < 2; ++k) dst[m][k] = *(const LAS bf16x8*)(lds + PG8_SA(b, h) + aoff + m * 2048 + k * 1024); } while (0)
; #define PG8_LDB(dst, b, h) do { _Pragma("unroll") for (int n = 0; n < 2; ++n) _Pragma("unroll") for (int k = 0; k < 2; ++k) dst[n][k] = *(const LAS bf16x8*)(lds + PG8_SB(b, h) + boff + n * 2048 + k * 1024); } while (0)
; #define PG8_WAIT_V(n) asm volatile("s_waitcnt vmcnt(" #n ")" ::: "memory")
; #define PG8_WAIT_L(n) asm volatile("s_waitcnt lgkmcnt(" #n ")" ::: "memory")
; #define PG8_BAR __builtin_amdgcn_s_barrier()
; #define PG8_SCHED __builtin_amdgcn_sched_barrier(0)
; template <class Epi, int LDA, int LDB, int KK>
; __device__ __forceinline__ void gemm_phase(int wv, LAS unsigned char* lds, const Gemm g, const StaticOrder& S, const Epi& E) {
;     ...
;             PG8_LDB(B0, 0, 0); PG8_SCHED; PG8_LDA(At, 0, 0); PG8_STAGE(PG8_SA(1, 1), a1 + hstepA, voffA);
;             PG8_WAIT_L(8); PG8_BAR; PG8_WAIT_L(0); PG8_MMA(0, 0, At, B0); PG8_BAR; PG8_SCHED;
;             PG8_LDB(B1, 0, 1); PG8_STAGE(PG8_SB(0, 0), b2, voffB);
;             PG8_BAR; PG8_WAIT_L(0); PG8_MMA(0, 1, At, B1); PG8_BAR;
;             PG8_LDA(At, 0, 1); PG8_STAGE(PG8_SA(0, 0), a2, voffA);
;             PG8_BAR; PG8_WAIT_L(0); PG8_MMA(1, 0, At, B0); PG8_BAR; PG8_SCHED;
;             PG8_STAGE(PG8_SB(0, 1), b2 + hstepB, voffB);
;             PG8_WAIT_V(6); PG8_BAR; PG8_MMA(1, 1, At, B1); PG8_BAR;
;             PG8_LDB(B0, 1, 0); PG8_SCHED; PG8_LDA(At, 1, 0); PG8_STAGE(PG8_SA(0, 1), a2 + hstepA, voffA);
;             PG8_WAIT_L(8); PG8_BAR; PG8_WAIT_L(0); PG8_MMA(0, 0, At, B0); PG8_BAR; PG8_SCHED;
;             PG8_LDB(B1, 1, 1); PG8_STAGE(PG8_SB(1, 0), b3, voffB);
;             PG8_BAR; PG8_WAIT_L(0); PG8_MMA(0, 1, At, B1); PG8_BAR;
;             PG8_LDA(At, 1, 1); PG8_STAGE(PG8_SA(1, 0), a3, voffA);
;             PG8_BAR; PG8_WAIT_L(0); PG8_MMA(1, 0, At, B0); PG8_BAR; PG8_SCHED;
;             PG8_STAGE(PG8_SB(1, 1), b3 + hstepB, voffB);
;             PG8_WAIT_V(6); PG8_BAR; PG8_MMA(1, 1, At, B1); PG8_BAR;
	v_mfma_f32_16x16x32_bf16 v[64:67], v[202:205], v[164:167], v[64:67]
	ds_read_b128 v[132:135], v180 offset:32768
	v_mfma_f32_16x16x32_bf16 v[60:63], v[206:209], v[164:167], v[60:63]
	ds_read_b128 v[136:139], v180 offset:34816
	v_mfma_f32_16x16x32_bf16 v[56:59], v[210:213], v[164:167], v[56:59]
	ds_read_b128 v[140:143], v180 offset:49152
	v_mfma_f32_16x16x32_bf16 v[52:55], v[214:217], v[164:167], v[52:55]
	ds_read_b128 v[144:147], v180 offset:51200
	v_mfma_f32_16x16x32_bf16 v[48:51], v[202:205], v[168:171], v[48:51]
	ds_read_b128 v[148:151], v234 offset:32768
	v_mfma_f32_16x16x32_bf16 v[44:47], v[206:209], v[168:171], v[44:47]
	ds_read_b128 v[152:155], v234 offset:34816
	v_mfma_f32_16x16x32_bf16 v[40:43], v[210:213], v[168:171], v[40:43]
	ds_read_b128 v[156:159], v234 offset:36864
	v_mfma_f32_16x16x32_bf16 v[36:39], v[214:217], v[168:171], v[36:39]
	ds_read_b128 v[160:163], v234 offset:38912
	v_mfma_f32_16x16x32_bf16 v[32:35], v[202:205], v[172:175], v[32:35]
	s_add_u32 s98, s28, 0x80000
	s_addc_u32 s99, s29, 0
	s_add_i32 m0, s40, 0x4000
	v_mfma_f32_16x16x32_bf16 v[28:31], v[206:209], v[172:175], v[28:31]
	global_load_lds_dwordx4 v190, s[98:99]
	v_mfma_f32_16x16x32_bf16 v[24:27], v[210:213], v[172:175], v[24:27]
	v_mfma_f32_16x16x32_bf16 v[20:23], v[214:217], v[172:175], v[20:23]
	s_add_i32 m0, s40, 0x6000
	v_mfma_f32_16x16x32_bf16 v[16:19], v[202:205], v[176:179], v[16:19]
	global_load_lds_dwordx4 v188, s[98:99]
	v_mfma_f32_16x16x32_bf16 v[12:15], v[206:209], v[176:179], v[12:15]
	v_mfma_f32_16x16x32_bf16 v[8:11], v[210:213], v[176:179], v[8:11]
	v_mfma_f32_16x16x32_bf16 v[4:7], v[214:217], v[176:179], v[4:7]
	s_add_u32 s26, s26, 0x80
	s_addc_u32 s27, s27, 0
	s_add_u32 s28, s28, 0x80
	s_addc_u32 s29, s29, 0
	s_waitcnt lgkmcnt(0)
	v_mfma_f32_16x16x32_bf16 v[128:131], v[132:135], v[148:151], v[128:131]
	ds_read_b128 v[202:205], v180 offset:33792
	v_mfma_f32_16x16x32_bf16 v[124:127], v[136:139], v[148:151], v[124:127]
	ds_read_b128 v[206:209], v180 offset:35840
	v_mfma_f32_16x16x32_bf16 v[120:123], v[140:143], v[148:151], v[120:123]
	ds_read_b128 v[210:213], v180 offset:50176
	v_mfma_f32_16x16x32_bf16 v[116:119], v[144:147], v[148:151], v[116:119]
	ds_read_b128 v[214:217], v180 offset:52224
	v_mfma_f32_16x16x32_bf16 v[112:115], v[132:135], v[152:155], v[112:115]
	ds_read_b128 v[164:167], v234 offset:33792
	v_mfma_f32_16x16x32_bf16 v[108:111], v[136:139], v[152:155], v[108:111]
	ds_read_b128 v[168:171], v234 offset:35840
	v_mfma_f32_16x16x32_bf16 v[104:107], v[140:143], v[152:155], v[104:107]
	ds_read_b128 v[172:175], v234 offset:37888
	v_mfma_f32_16x16x32_bf16 v[100:103], v[144:147], v[152:155], v[100:103]
	ds_read_b128 v[176:179], v234 offset:39936
	v_mfma_f32_16x16x32_bf16 v[96:99], v[132:135], v[156:159], v[96:99]
	v_mfma_f32_16x16x32_bf16 v[92:95], v[136:139], v[156:159], v[92:95]
	v_mfma_f32_16x16x32_bf16 v[88:91], v[140:143], v[156:159], v[88:91]
	v_mfma_f32_16x16x32_bf16 v[84:87], v[144:147], v[156:159], v[84:87]
	v_mfma_f32_16x16x32_bf16 v[80:83], v[132:135], v[160:163], v[80:83]
	v_mfma_f32_16x16x32_bf16 v[76:79], v[136:139], v[160:163], v[76:79]
	v_mfma_f32_16x16x32_bf16 v[72:75], v[140:143], v[160:163], v[72:75]
	v_mfma_f32_16x16x32_bf16 v[68:71], v[144:147], v[160:163], v[68:71]
	s_waitcnt vmcnt(8) lgkmcnt(0)
	s_barrier
	v_mfma_f32_16x16x32_bf16 v[128:131], v[202:205], v[164:167], v[128:131]
	ds_read_b128 v[148:151], v234 offset:49152
	v_mfma_f32_16x16x32_bf16 v[124:127], v[206:209], v[164:167], v[124:127]
	ds_read_b128 v[152:155], v234 offset:51200
	v_mfma_f32_16x16x32_bf16 v[120:123], v[210:213], v[164:167], v[120:123]
	ds_read_b128 v[156:159], v234 offset:53248
	v_mfma_f32_16x16x32_bf16 v[116:119], v[214:217], v[164:167], v[116:119]
	ds_read_b128 v[160:163], v234 offset:55296
	v_mfma_f32_16x16x32_bf16 v[112:115], v[202:205], v[168:171], v[112:115]
	s_add_i32 m0, s40, 0x18000
	v_mfma_f32_16x16x32_bf16 v[108:111], v[206:209], v[168:171], v[108:111]
	global_load_lds_dwordx4 v2, s[26:27]
	v_mfma_f32_16x16x32_bf16 v[104:107], v[210:213], v[168:171], v[104:107]
	v_mfma_f32_16x16x32_bf16 v[100:103], v[214:217], v[168:171], v[100:103]
	s_add_i32 m0, s40, 0x1a000
	v_mfma_f32_16x16x32_bf16 v[96:99], v[202:205], v[172:175], v[96:99]
	global_load_lds_dwordx4 v0, s[26:27]
	v_mfma_f32_16x16x32_bf16 v[92:95], v[206:209], v[172:175], v[92:95]
	v_mfma_f32_16x16x32_bf16 v[88:91], v[210:213], v[172:175], v[88:91]
	s_add_i32 m0, s40, 0x8000
	v_mfma_f32_16x16x32_bf16 v[84:87], v[214:217], v[172:175], v[84:87]
	global_load_lds_dwordx4 v190, s[28:29]
	v_mfma_f32_16x16x32_bf16 v[80:83], v[202:205], v[176:179], v[80:83]
	v_mfma_f32_16x16x32_bf16 v[76:79], v[206:209], v[176:179], v[76:79]
	v_mfma_f32_16x16x32_bf16 v[72:75], v[210:213], v[176:179], v[72:75]
	v_mfma_f32_16x16x32_bf16 v[68:71], v[214:217], v[176:179], v[68:71]
	s_waitcnt lgkmcnt(0)
	v_mfma_f32_16x16x32_bf16 v[64:67], v[132:135], v[148:151], v[64:67]
	ds_read_b128 v[164:167], v234 offset:50176
	v_mfma_f32_16x16x32_bf16 v[60:63], v[136:139], v[148:151], v[60:63]
	ds_read_b128 v[168:171], v234 offset:52224
	v_mfma_f32_16x16x32_bf16 v[56:59], v[140:143], v[148:151], v[56:59]
	ds_read_b128 v[172:175], v234 offset:54272
	v_mfma_f32_16x16x32_bf16 v[52:55], v[144:147], v[148:151], v[52:55]
	ds_read_b128 v[176:179], v234 offset:56320
	v_mfma_f32_16x16x32_bf16 v[48:51], v[132:135], v[152:155], v[48:51]
	s_add_i32 m0, s40, 0xa000
	v_mfma_f32_16x16x32_bf16 v[44:47], v[136:139], v[152:155], v[44:47]
	global_load_lds_dwordx4 v188, s[28:29]
	v_mfma_f32_16x16x32_bf16 v[40:43], v[140:143], v[152:155], v[40:43]
	v_mfma_f32_16x16x32_bf16 v[36:39], v[144:147], v[152:155], v[36:39]
	s_add_u32 s98, s26, 0x80000
	s_addc_u32 s99, s27, 0
	s_add_i32 m0, s40, 0x1c000
	v_mfma_f32_16x16x32_bf16 v[32:35], v[132:135], v[156:159], v[32:35]
	global_load_lds_dwordx4 v2, s[98:99]
	v_mfma_f32_16x16x32_bf16 v[28:31], v[136:139], v[156:159], v[28:31]
	v_mfma_f32_16x16x32_bf16 v[24:27], v[140:143], v[156:159], v[24:27]
	s_add_i32 m0, s40, 0x1e000
	v_mfma_f32_16x16x32_bf16 v[20:23], v[144:147], v[156:159], v[20:23]
	global_load_lds_dwordx4 v0, s[98:99]
	v_mfma_f32_16x16x32_bf16 v[16:19], v[132:135], v[160:163], v[16:19]
	v_mfma_f32_16x16x32_bf16 v[12:15], v[136:139], v[160:163], v[12:15]
	v_mfma_f32_16x16x32_bf16 v[8:11], v[140:143], v[160:163], v[8:11]
	v_mfma_f32_16x16x32_bf16 v[4:7], v[144:147], v[160:163], v[4:7]
	s_waitcnt vmcnt(8) lgkmcnt(0)
	s_barrier
; #define LAS __attribute__((address_space(3)))
; #define PG8_STAGE(bufoff, gbase, voff) do { _Pragma("unroll") for (int _i = 0; _i < 2; ++_i) \
;         __builtin_amdgcn_global_load_lds((const unsigned*)((const char*)(gbase) + (voff)[_i]), (LAS unsigned*)(lds + (bufoff) + ldsw + _i * 8192), 16, 0, 0); } while (0)
; #define PG8_LDA(dst, b, h) do { _Pragma("unroll") for (int m = 0; m < 4; ++m) _Pragma("unroll") for (int k = 0; k < 2; ++k) dst[m][k] = *(const LAS bf16x8*)(lds + PG8_SA(b, h) + aoff + m * 2048 + k * 1024); } while (0)
; #define PG8_MMA(ai, bj, At, Bt) do { __builtin_amdgcn_s_setprio(1); _Pragma("unroll") for (int m = 0; m < 4; ++m) _Pragma("unroll") for (int n = 0; n < 2; ++n) _Pragma("unroll") for (int k = 0; k < 2; ++k) \
;         acc[ai][bj][m][n] = __builtin_amdgcn_mfma_f32_16x16x32_bf16(Bt[n][k], At[m][k], acc[ai][bj][m][n], 0, 0, 0); __builtin_amdgcn_s_setprio(0); } while (0)
; #define PG8_WAIT_V(n) asm volatile("s_waitcnt vmcnt(" #n ")" ::: "memory")
; #define PG8_WAIT_L(n) asm volatile("s_waitcnt lgkmcnt(" #n ")" ::: "memory")
; #define PG8_BAR __builtin_amdgcn_s_barrier()
; #define PG8_SCHED __builtin_amdgcn_sched_barrier(0)
; template <class Epi, int LDA, int LDB, int KK>
; __device__ __forceinline__ void gemm_phase(int wv, LAS unsigned char* lds, const Gemm g, const StaticOrder& S, const Epi& E) {
;     ...
;             PG8_LDA(At, 1, 1); PG8_STAGE(PG8_SA(1, 0), a3, voffA);
;             PG8_BAR; PG8_WAIT_L(0); PG8_MMA(1, 0, At, B0); PG8_BAR; PG8_SCHED;
;             PG8_STAGE(PG8_SB(1, 1), b3 + hstepB, voffB);
;             PG8_WAIT_V(6); PG8_BAR; PG8_MMA(1, 1, At, B1); PG8_BAR;
;           }
;           if constexpr (Epi::HAS_MID) { if (seg < Epi::NSEG - 1) E.mid(acc, cur, seg, wr, wc, fr, fq); }
;         }
;         E(acc, cur, wr, wc, fr, fq, (const LAS float*)(lds + 131072 + (ui % 3) * 1024));
;         if (!has_next) break;
	v_mfma_f32_16x16x32_bf16 v[64:67], v[202:205], v[164:167], v[64:67]
	ds_read_b128 v[132:135], v180 offset:0
	v_mfma_f32_16x16x32_bf16 v[60:63], v[206:209], v[164:167], v[60:63]
	ds_read_b128 v[136:139], v180 offset:2048
	v_mfma_f32_16x16x32_bf16 v[56:59], v[210:213], v[164:167], v[56:59]
	ds_read_b128 v[140:143], v180 offset:16384
	v_mfma_f32_16x16x32_bf16 v[52:55], v[214:217], v[164:167], v[52:55]
	ds_read_b128 v[144:147], v180 offset:18432
	v_mfma_f32_16x16x32_bf16 v[48:51], v[202:205], v[168:171], v[48:51]
	ds_read_b128 v[148:151], v234 offset:0
	v_mfma_f32_16x16x32_bf16 v[44:47], v[206:209], v[168:171], v[44:47]
	ds_read_b128 v[152:155], v234 offset:2048
	v_mfma_f32_16x16x32_bf16 v[40:43], v[210:213], v[168:171], v[40:43]
	ds_read_b128 v[156:159], v234 offset:4096
	v_mfma_f32_16x16x32_bf16 v[36:39], v[214:217], v[168:171], v[36:39]
	ds_read_b128 v[160:163], v234 offset:6144
	v_mfma_f32_16x16x32_bf16 v[32:35], v[202:205], v[172:175], v[32:35]
	s_add_u32 s98, s28, 0x80000
	s_addc_u32 s99, s29, 0
	s_add_i32 m0, s40, 0xc000
	v_mfma_f32_16x16x32_bf16 v[28:31], v[206:209], v[172:175], v[28:31]
	global_load_lds_dwordx4 v190, s[98:99]
	v_mfma_f32_16x16x32_bf16 v[24:27], v[210:213], v[172:175], v[24:27]
	v_mfma_f32_16x16x32_bf16 v[20:23], v[214:217], v[172:175], v[20:23]
	s_add_i32 m0, s40, 0xe000
	v_mfma_f32_16x16x32_bf16 v[16:19], v[202:205], v[176:179], v[16:19]
	global_load_lds_dwordx4 v188, s[98:99]
	v_mfma_f32_16x16x32_bf16 v[12:15], v[206:209], v[176:179], v[12:15]
	v_mfma_f32_16x16x32_bf16 v[8:11], v[210:213], v[176:179], v[8:11]
	v_mfma_f32_16x16x32_bf16 v[4:7], v[214:217], v[176:179], v[4:7]
	s_add_i32 s69, s69, 2
	s_add_u32 s56, s56, 0x100
	s_addc_u32 s68, s68, 0
	s_add_u32 s24, s24, 0x100
	s_addc_u32 s25, s25, 0
	s_cmp_gt_u32 s69, 29
	s_cbranch_scc0 .Lout_loop
	s_waitcnt lgkmcnt(0)
	s_cmp_eq_u32 s100, 0
	s_cbranch_scc1 .Lot_epi
	s_cmp_eq_u32 s100, 4
	s_cbranch_scc1 .Lot_owner
	s_and_b32 s98, s81, 15
	s_mul_i32 s98, s98, 3
	s_add_u32 s98, s98, s100
	s_sub_u32 s98, s98, 1
	s_lshl_b32 s98, s98, 18
	s_add_u32 s98, s98, 0x1f000000
	s_add_u32 s98, s10, s98
	s_addc_u32 s99, s11, 0
	v_mbcnt_lo_u32_b32 v132, -1, 0
	v_mbcnt_hi_u32_b32 v132, -1, v132
	v_lshl_or_b32 v132, s95, 6, v132
	v_lshlrev_b32_e32 v132, 4, v132
	global_store_dwordx4 v132, v[4:7], s[98:99] sc0 sc1
	v_add_u32_e32 v132, 0x2000, v132
	global_store_dwordx4 v132, v[8:11], s[98:99] sc0 sc1
	v_add_u32_e32 v132, 0x2000, v132
	global_store_dwordx4 v132, v[12:15], s[98:99] sc0 sc1
	v_add_u32_e32 v132, 0x2000, v132
	global_store_dwordx4 v132, v[16:19], s[98:99] sc0 sc1
	v_add_u32_e32 v132, 0x2000, v132
	global_store_dwordx4 v132, v[20:23], s[98:99] sc0 sc1
	v_add_u32_e32 v132, 0x2000, v132
	global_store_dwordx4 v132, v[24:27], s[98:99] sc0 sc1
	v_add_u32_e32 v132, 0x2000, v132
	global_store_dwordx4 v132, v[28:31], s[98:99] sc0 sc1
	v_add_u32_e32 v132, 0x2000, v132
	global_store_dwordx4 v132, v[32:35], s[98:99] sc0 sc1
	v_add_u32_e32 v132, 0x2000, v132
	global_store_dwordx4 v132, v[36:39], s[98:99] sc0 sc1
	v_add_u32_e32 v132, 0x2000, v132
	global_store_dwordx4 v132, v[40:43], s[98:99] sc0 sc1
	v_add_u32_e32 v132, 0x2000, v132
	global_store_dwordx4 v132, v[44:47], s[98:99] sc0 sc1
	v_add_u32_e32 v132, 0x2000, v132
	global_store_dwordx4 v132, v[48:51], s[98:99] sc0 sc1
	v_add_u32_e32 v132, 0x2000, v132
	global_store_dwordx4 v132, v[52:55], s[98:99] sc0 sc1
	v_add_u32_e32 v132, 0x2000, v132
	global_store_dwordx4 v132, v[56:59], s[98:99] sc0 sc1
	v_add_u32_e32 v132, 0x2000, v132
	global_store_dwordx4 v132, v[60:63], s[98:99] sc0 sc1
	v_add_u32_e32 v132, 0x2000, v132
	global_store_dwordx4 v132, v[64:67], s[98:99] sc0 sc1
	v_add_u32_e32 v132, 0x2000, v132
	global_store_dwordx4 v132, v[68:71], s[98:99] sc0 sc1
	v_add_u32_e32 v132, 0x2000, v132
	global_store_dwordx4 v132, v[72:75], s[98:99] sc0 sc1
	v_add_u32_e32 v132, 0x2000, v132
	global_store_dwordx4 v132, v[76:79], s[98:99] sc0 sc1
	v_add_u32_e32 v132, 0x2000, v132
	global_store_dwordx4 v132, v[80:83], s[98:99] sc0 sc1
	v_add_u32_e32 v132, 0x2000, v132
	global_store_dwordx4 v132, v[84:87], s[98:99] sc0 sc1
	v_add_u32_e32 v132, 0x2000, v132
	global_store_dwordx4 v132, v[88:91], s[98:99] sc0 sc1
	v_add_u32_e32 v132, 0x2000, v132
	global_store_dwordx4 v132, v[92:95], s[98:99] sc0 sc1
	v_add_u32_e32 v132, 0x2000, v132
	global_store_dwordx4 v132, v[96:99], s[98:99] sc0 sc1
	v_add_u32_e32 v132, 0x2000, v132
	global_store_dwordx4 v132, v[100:103], s[98:99] sc0 sc1
	v_add_u32_e32 v132, 0x2000, v132
	global_store_dwordx4 v132, v[104:107], s[98:99] sc0 sc1
	v_add_u32_e32 v132, 0x2000, v132
	global_store_dwordx4 v132, v[108:111], s[98:99] sc0 sc1
	v_add_u32_e32 v132, 0x2000, v132
	global_store_dwordx4 v132, v[112:115], s[98:99] sc0 sc1
	v_add_u32_e32 v132, 0x2000, v132
	global_store_dwordx4 v132, v[116:119], s[98:99] sc0 sc1
	v_add_u32_e32 v132, 0x2000, v132
	global_store_dwordx4 v132, v[120:123], s[98:99] sc0 sc1
	v_add_u32_e32 v132, 0x2000, v132
	global_store_dwordx4 v132, v[124:127], s[98:99] sc0 sc1
	v_add_u32_e32 v132, 0x2000, v132
	global_store_dwordx4 v132, v[128:131], s[98:99] sc0 sc1
	s_waitcnt vmcnt(0)
	s_barrier
	s_cmp_lg_u32 s95, 0
	s_cbranch_scc1 .Lot_p_done
	s_and_b32 s98, s81, 15
	s_lshl_b32 s98, s98, 2
	s_add_u32 s98, s98, 0x285da940
	s_add_u32 s98, s10, s98
	s_addc_u32 s99, s11, 0
	s_mov_b64 exec, 1
	v_mov_b32_e32 v132, 0
	v_mov_b32_e32 v133, 1
	global_atomic_add v132, v133, s[98:99]
	s_mov_b64 exec, -1

; #define PG8_STAGE(bufoff, gbase, voff) do { _Pragma("unroll") for (int _i = 0; _i < 2; ++_i) \
;         __builtin_amdgcn_global_load_lds((const unsigned*)((const char*)(gbase) + (voff)[_i]), (LAS unsigned*)(lds + (bufoff) + ldsw + _i * 8192), 16, 0, 0); } while (0)
; #define PG8_LDA(dst, b, h) do { _Pragma("unroll") for (int m = 0; m < 4; ++m) _Pragma("unroll") for (int k = 0; k < 2; ++k) dst[m][k] = *(const LAS bf16x8*)(lds + PG8_SA(b, h) + aoff + m * 2048 + k * 1024); } while (0)
; #define PG8_WAIT_V(n) asm volatile("s_waitcnt vmcnt(" #n ")" ::: "memory")
; #define PG8_BAR __builtin_amdgcn_s_barrier()
; template <class Epi, int LDA, int LDB, int KK>
; __device__ __forceinline__ void gemm_phase(int wv, LAS unsigned char* lds, const Gemm g, const StaticOrder& S, const Epi& E) {
;     ...
;           for (; t < tend; t += 2) {
;             const bool last = (t == nt - 2);
;             const char* a1 = cA + (size_t)(t + 1) * kstep;
;             const char* a2 = last ? nA : cA + (size_t)(t + 2) * kstep; const char* b2 = last ? nB : cB + (size_t)(t + 2) * kstep;
;             const char* a3 = a2 + kstep; const char* b3 = b2 + kstep;
;             PG8_LDB(B0, 0, 0); PG8_SCHED; PG8_LDA(At, 0, 0); PG8_STAGE(PG8_SA(1, 1), a1 + hstepA, voffA);
;             PG8_WAIT_L(8); PG8_BAR; PG8_WAIT_L(0); PG8_MMA(0, 0, At, B0); PG8_BAR; PG8_SCHED;
;             PG8_LDB(B1, 0, 1); PG8_STAGE(PG8_SB(0, 0), b2, voffB);
;             PG8_BAR; PG8_WAIT_L(0); PG8_MMA(0, 1, At, B1); PG8_BAR;
;             PG8_LDA(At, 0, 1); PG8_STAGE(PG8_SA(0, 0), a2, voffA);
;             PG8_BAR; PG8_WAIT_L(0); PG8_MMA(1, 0, At, B0); PG8_BAR; PG8_SCHED;
;             PG8_STAGE(PG8_SB(0, 1), b2 + hstepB, voffB);
;             PG8_WAIT_V(6); PG8_BAR; PG8_MMA(1, 1, At, B1); PG8_BAR;
;             PG8_LDB(B0, 1, 0); PG8_SCHED; PG8_LDA(At, 1, 0); PG8_STAGE(PG8_SA(0, 1), a2 + hstepA, voffA);
;             PG8_WAIT_L(8); PG8_BAR; PG8_WAIT_L(0); PG8_MMA(0, 0, At, B0); PG8_BAR; PG8_SCHED;
;             PG8_LDB(B1, 1, 1); PG8_STAGE(PG8_SB(1, 0), b3, voffB);
;             PG8_BAR; PG8_WAIT_L(0); PG8_MMA(0, 1, At, B1); PG8_BAR;
;             PG8_LDA(At, 1, 1); PG8_STAGE(PG8_SA(1, 0), a3, voffA);
;             PG8_BAR; PG8_WAIT_L(0); PG8_MMA(1, 0, At, B0); PG8_BAR; PG8_SCHED;
;             PG8_STAGE(PG8_SB(1, 1), b3 + hstepB, voffB);
;             PG8_WAIT_V(6); PG8_BAR; PG8_MMA(1, 1, At, B1); PG8_BAR;
.Lup_loop:
	s_add_u32 s26, s6, 0xfff80080
	s_addc_u32 s27, s7, -1
	s_cmp_eq_u32 s56, 28
	s_cselect_b32 s29, s17, s27
	s_cselect_b32 s28, s45, s26
	s_cselect_b32 s27, s15, s55
	s_cselect_b32 s26, s46, s47
	s_waitcnt lgkmcnt(0)
	v_mfma_f32_16x16x32_bf16 v[128:131], v[148:151], v[164:167], v[128:131]
	ds_read_b128 v[202:205], v147 offset:1024
	v_mfma_f32_16x16x32_bf16 v[124:127], v[152:155], v[164:167], v[124:127]
	ds_read_b128 v[206:209], v147 offset:3072
	v_mfma_f32_16x16x32_bf16 v[120:123], v[156:159], v[164:167], v[120:123]
	ds_read_b128 v[210:213], v147 offset:17408
	v_mfma_f32_16x16x32_bf16 v[116:119], v[160:163], v[164:167], v[116:119]
	ds_read_b128 v[214:217], v147 offset:19456
	v_mfma_f32_16x16x32_bf16 v[112:115], v[148:151], v[168:171], v[112:115]
	ds_read_b128 v[180:183], v146 offset:1024
	v_mfma_f32_16x16x32_bf16 v[108:111], v[152:155], v[168:171], v[108:111]
	ds_read_b128 v[184:187], v146 offset:3072
	v_mfma_f32_16x16x32_bf16 v[104:107], v[156:159], v[168:171], v[104:107]
	ds_read_b128 v[188:191], v146 offset:5120
	v_mfma_f32_16x16x32_bf16 v[100:103], v[160:163], v[168:171], v[100:103]
	ds_read_b128 v[192:195], v146 offset:7168
	v_mfma_f32_16x16x32_bf16 v[96:99], v[148:151], v[172:175], v[96:99]
	v_mfma_f32_16x16x32_bf16 v[92:95], v[152:155], v[172:175], v[92:95]
	v_mfma_f32_16x16x32_bf16 v[88:91], v[156:159], v[172:175], v[88:91]
	v_mfma_f32_16x16x32_bf16 v[84:87], v[160:163], v[172:175], v[84:87]
	v_mfma_f32_16x16x32_bf16 v[80:83], v[148:151], v[176:179], v[80:83]
	v_mfma_f32_16x16x32_bf16 v[76:79], v[152:155], v[176:179], v[76:79]
	v_mfma_f32_16x16x32_bf16 v[72:75], v[156:159], v[176:179], v[72:75]
	v_mfma_f32_16x16x32_bf16 v[68:71], v[160:163], v[176:179], v[68:71]
	s_waitcnt vmcnt(8) lgkmcnt(0)
	s_barrier
	v_mfma_f32_16x16x32_bf16 v[128:131], v[202:205], v[180:183], v[128:131]
	ds_read_b128 v[164:167], v146 offset:16384
	v_mfma_f32_16x16x32_bf16 v[124:127], v[206:209], v[180:183], v[124:127]
	ds_read_b128 v[168:171], v146 offset:18432
	v_mfma_f32_16x16x32_bf16 v[120:123], v[210:213], v[180:183], v[120:123]
	ds_read_b128 v[172:175], v146 offset:20480
	v_mfma_f32_16x16x32_bf16 v[116:119], v[214:217], v[180:183], v[116:119]
	ds_read_b128 v[176:179], v146 offset:22528
	v_mfma_f32_16x16x32_bf16 v[112:115], v[202:205], v[184:187], v[112:115]
	s_add_i32 m0, s25, 0x10000
	v_mfma_f32_16x16x32_bf16 v[108:111], v[206:209], v[184:187], v[108:111]
	global_load_lds_dwordx4 v2, s[26:27]
	v_mfma_f32_16x16x32_bf16 v[104:107], v[210:213], v[184:187], v[104:107]
	v_mfma_f32_16x16x32_bf16 v[100:103], v[214:217], v[184:187], v[100:103]
	s_add_i32 m0, s25, 0x12000
	v_mfma_f32_16x16x32_bf16 v[96:99], v[202:205], v[188:191], v[96:99]
	global_load_lds_dwordx4 v134, s[26:27]
	v_mfma_f32_16x16x32_bf16 v[92:95], v[206:209], v[188:191], v[92:95]
	v_mfma_f32_16x16x32_bf16 v[88:91], v[210:213], v[188:191], v[88:91]
	s_mov_b32 m0, s25
	v_mfma_f32_16x16x32_bf16 v[84:87], v[214:217], v[188:191], v[84:87]
	global_load_lds_dwordx4 v0, s[28:29]
	v_mfma_f32_16x16x32_bf16 v[80:83], v[202:205], v[192:195], v[80:83]
	v_mfma_f32_16x16x32_bf16 v[76:79], v[206:209], v[192:195], v[76:79]
	v_mfma_f32_16x16x32_bf16 v[72:75], v[210:213], v[192:195], v[72:75]
	v_mfma_f32_16x16x32_bf16 v[68:71], v[214:217], v[192:195], v[68:71]
	s_waitcnt lgkmcnt(0)
	v_mfma_f32_16x16x32_bf16 v[64:67], v[148:151], v[164:167], v[64:67]
	ds_read_b128 v[180:183], v146 offset:17408
	v_mfma_f32_16x16x32_bf16 v[60:63], v[152:155], v[164:167], v[60:63]
	ds_read_b128 v[184:187], v146 offset:19456
	v_mfma_f32_16x16x32_bf16 v[56:59], v[156:159], v[164:167], v[56:59]
	ds_read_b128 v[188:191], v146 offset:21504
	v_mfma_f32_16x16x32_bf16 v[52:55], v[160:163], v[164:167], v[52:55]
	ds_read_b128 v[192:195], v146 offset:23552
	v_mfma_f32_16x16x32_bf16 v[48:51], v[148:151], v[168:171], v[48:51]
	s_add_i32 m0, s25, 0x2000
	v_mfma_f32_16x16x32_bf16 v[44:47], v[152:155], v[168:171], v[44:47]
	global_load_lds_dwordx4 v132, s[28:29]
	v_mfma_f32_16x16x32_bf16 v[40:43], v[156:159], v[168:171], v[40:43]
	v_mfma_f32_16x16x32_bf16 v[36:39], v[160:163], v[168:171], v[36:39]
	s_add_u32 s98, s26, 0x80000
	s_addc_u32 s99, s27, 0
	s_add_i32 m0, s25, 0x14000
	v_mfma_f32_16x16x32_bf16 v[32:35], v[148:151], v[172:175], v[32:35]
	global_load_lds_dwordx4 v2, s[98:99]
	v_mfma_f32_16x16x32_bf16 v[28:31], v[152:155], v[172:175], v[28:31]
	v_mfma_f32_16x16x32_bf16 v[24:27], v[156:159], v[172:175], v[24:27]
	s_add_i32 m0, s25, 0x16000
	v_mfma_f32_16x16x32_bf16 v[20:23], v[160:163], v[172:175], v[20:23]
	global_load_lds_dwordx4 v134, s[98:99]
	v_mfma_f32_16x16x32_bf16 v[16:19], v[148:151], v[176:179], v[16:19]
	v_mfma_f32_16x16x32_bf16 v[12:15], v[152:155], v[176:179], v[12:15]
	v_mfma_f32_16x16x32_bf16 v[8:11], v[156:159], v[176:179], v[8:11]
	v_mfma_f32_16x16x32_bf16 v[4:7], v[160:163], v[176:179], v[4:7]
	s_waitcnt vmcnt(8) lgkmcnt(0)
	s_barrier
; #define PG8_STAGE(bufoff, gbase, voff) do { _Pragma("unroll") for (int _i = 0; _i < 2; ++_i) \
;         __builtin_amdgcn_global_load_lds((const unsigned*)((const char*)(gbase) + (voff)[_i]), (LAS unsigned*)(lds + (bufoff) + ldsw + _i * 8192), 16, 0, 0); } while (0)
; #define PG8_LDA(dst, b, h) do { _Pragma("unroll") for (int m = 0; m < 4; ++m) _Pragma("unroll") for (int k = 0; k < 2; ++k) dst[m][k] = *(const LAS bf16x8*)(lds + PG8_SA(b, h) + aoff + m * 2048 + k * 1024); } while (0)
; #define PG8_LDB(dst, b, h) do { _Pragma("unroll") for (int n = 0; n < 2; ++n) _Pragma("unroll") for (int k = 0; k < 2; ++k) dst[n][k] = *(const LAS bf16x8*)(lds + PG8_SB(b, h) + boff + n * 2048 + k * 1024); } while (0)
; #define PG8_WAIT_V(n) asm volatile("s_waitcnt vmcnt(" #n ")" ::: "memory")
; #define PG8_WAIT_L(n) asm volatile("s_waitcnt lgkmcnt(" #n ")" ::: "memory")
; #define PG8_BAR __builtin_amdgcn_s_barrier()
; #define PG8_SCHED __builtin_amdgcn_sched_barrier(0)
; template <class Epi, int LDA, int LDB, int KK>
; __device__ __forceinline__ void gemm_phase(int wv, LAS unsigned char* lds, const Gemm g, const StaticOrder& S, const Epi& E) {
;     ...
;             PG8_LDB(B0, 0, 0); PG8_SCHED; PG8_LDA(At, 0, 0); PG8_STAGE(PG8_SA(1, 1), a1 + hstepA, voffA);
;             PG8_WAIT_L(8); PG8_BAR; PG8_WAIT_L(0); PG8_MMA(0, 0, At, B0); PG8_BAR; PG8_SCHED;
;             PG8_LDB(B1, 0, 1); PG8_STAGE(PG8_SB(0, 0), b2, voffB);
;             PG8_BAR; PG8_WAIT_L(0); PG8_MMA(0, 1, At, B1); PG8_BAR;
;             PG8_LDA(At, 0, 1); PG8_STAGE(PG8_SA(0, 0), a2, voffA);
;             PG8_BAR; PG8_WAIT_L(0); PG8_MMA(1, 0, At, B0); PG8_BAR; PG8_SCHED;
;             PG8_STAGE(PG8_SB(0, 1), b2 + hstepB, voffB);
;             PG8_WAIT_V(6); PG8_BAR; PG8_MMA(1, 1, At, B1); PG8_BAR;
;             PG8_LDB(B0, 1, 0); PG8_SCHED; PG8_LDA(At, 1, 0); PG8_STAGE(PG8_SA(0, 1), a2 + hstepA, voffA);
;             PG8_WAIT_L(8); PG8_BAR; PG8_WAIT_L(0); PG8_MMA(0, 0, At, B0); PG8_BAR; PG8_SCHED;
;             PG8_LDB(B1, 1, 1); PG8_STAGE(PG8_SB(1, 0), b3, voffB);
;             PG8_BAR; PG8_WAIT_L(0); PG8_MMA(0, 1, At, B1); PG8_BAR;
;             PG8_LDA(At, 1, 1); PG8_STAGE(PG8_SA(1, 0), a3, voffA);
;             PG8_BAR; PG8_WAIT_L(0); PG8_MMA(1, 0, At, B0); PG8_BAR; PG8_SCHED;
;             PG8_STAGE(PG8_SB(1, 1), b3 + hstepB, voffB);
;             PG8_WAIT_V(6); PG8_BAR; PG8_MMA(1, 1, At, B1); PG8_BAR;
	v_mfma_f32_16x16x32_bf16 v[64:67], v[202:205], v[180:183], v[64:67]
	ds_read_b128 v[148:151], v147 offset:32768
	v_mfma_f32_16x16x32_bf16 v[60:63], v[206:209], v[180:183], v[60:63]
	ds_read_b128 v[152:155], v147 offset:34816
	v_mfma_f32_16x16x32_bf16 v[56:59], v[210:213], v[180:183], v[56:59]
	ds_read_b128 v[156:159], v147 offset:49152
	v_mfma_f32_16x16x32_bf16 v[52:55], v[214:217], v[180:183], v[52:55]
	ds_read_b128 v[160:163], v147 offset:51200
	v_mfma_f32_16x16x32_bf16 v[48:51], v[202:205], v[184:187], v[48:51]
	ds_read_b128 v[164:167], v146 offset:32768
	v_mfma_f32_16x16x32_bf16 v[44:47], v[206:209], v[184:187], v[44:47]
	ds_read_b128 v[168:171], v146 offset:34816
	v_mfma_f32_16x16x32_bf16 v[40:43], v[210:213], v[184:187], v[40:43]
	ds_read_b128 v[172:175], v146 offset:36864
	v_mfma_f32_16x16x32_bf16 v[36:39], v[214:217], v[184:187], v[36:39]
	ds_read_b128 v[176:179], v146 offset:38912
	v_mfma_f32_16x16x32_bf16 v[32:35], v[202:205], v[188:191], v[32:35]
	s_add_u32 s98, s28, 0x80000
	s_addc_u32 s99, s29, 0
	s_add_i32 m0, s25, 0x4000
	v_mfma_f32_16x16x32_bf16 v[28:31], v[206:209], v[188:191], v[28:31]
	global_load_lds_dwordx4 v0, s[98:99]
	v_mfma_f32_16x16x32_bf16 v[24:27], v[210:213], v[188:191], v[24:27]
	v_mfma_f32_16x16x32_bf16 v[20:23], v[214:217], v[188:191], v[20:23]
	s_add_i32 m0, s25, 0x6000
	v_mfma_f32_16x16x32_bf16 v[16:19], v[202:205], v[192:195], v[16:19]
	global_load_lds_dwordx4 v132, s[98:99]
	v_mfma_f32_16x16x32_bf16 v[12:15], v[206:209], v[192:195], v[12:15]
	v_mfma_f32_16x16x32_bf16 v[8:11], v[210:213], v[192:195], v[8:11]
	v_mfma_f32_16x16x32_bf16 v[4:7], v[214:217], v[192:195], v[4:7]
	s_add_u32 s26, s26, 0x80
	s_addc_u32 s27, s27, 0
	s_add_u32 s28, s28, 0x80
	s_addc_u32 s29, s29, 0
	s_waitcnt lgkmcnt(0)
	v_mfma_f32_16x16x32_bf16 v[128:131], v[148:151], v[164:167], v[128:131]
	ds_read_b128 v[202:205], v147 offset:33792
	v_mfma_f32_16x16x32_bf16 v[124:127], v[152:155], v[164:167], v[124:127]
	ds_read_b128 v[206:209], v147 offset:35840
	v_mfma_f32_16x16x32_bf16 v[120:123], v[156:159], v[164:167], v[120:123]
	ds_read_b128 v[210:213], v147 offset:50176
	v_mfma_f32_16x16x32_bf16 v[116:119], v[160:163], v[164:167], v[116:119]
	ds_read_b128 v[214:217], v147 offset:52224
	v_mfma_f32_16x16x32_bf16 v[112:115], v[148:151], v[168:171], v[112:115]
	ds_read_b128 v[180:183], v146 offset:33792
	v_mfma_f32_16x16x32_bf16 v[108:111], v[152:155], v[168:171], v[108:111]
	ds_read_b128 v[184:187], v146 offset:35840
	v_mfma_f32_16x16x32_bf16 v[104:107], v[156:159], v[168:171], v[104:107]
	ds_read_b128 v[188:191], v146 offset:37888
	v_mfma_f32_16x16x32_bf16 v[100:103], v[160:163], v[168:171], v[100:103]
	ds_read_b128 v[192:195], v146 offset:39936
	v_mfma_f32_16x16x32_bf16 v[96:99], v[148:151], v[172:175], v[96:99]
	v_mfma_f32_16x16x32_bf16 v[92:95], v[152:155], v[172:175], v[92:95]
	v_mfma_f32_16x16x32_bf16 v[88:91], v[156:159], v[172:175], v[88:91]
	v_mfma_f32_16x16x32_bf16 v[84:87], v[160:163], v[172:175], v[84:87]
	v_mfma_f32_16x16x32_bf16 v[80:83], v[148:151], v[176:179], v[80:83]
	v_mfma_f32_16x16x32_bf16 v[76:79], v[152:155], v[176:179], v[76:79]
	v_mfma_f32_16x16x32_bf16 v[72:75], v[156:159], v[176:179], v[72:75]
	v_mfma_f32_16x16x32_bf16 v[68:71], v[160:163], v[176:179], v[68:71]
	s_waitcnt vmcnt(8) lgkmcnt(0)
	s_barrier
	v_mfma_f32_16x16x32_bf16 v[128:131], v[202:205], v[180:183], v[128:131]
	ds_read_b128 v[164:167], v146 offset:49152
	v_mfma_f32_16x16x32_bf16 v[124:127], v[206:209], v[180:183], v[124:127]
	ds_read_b128 v[168:171], v146 offset:51200
	v_mfma_f32_16x16x32_bf16 v[120:123], v[210:213], v[180:183], v[120:123]
	ds_read_b128 v[172:175], v146 offset:53248
	v_mfma_f32_16x16x32_bf16 v[116:119], v[214:217], v[180:183], v[116:119]
	ds_read_b128 v[176:179], v146 offset:55296
	v_mfma_f32_16x16x32_bf16 v[112:115], v[202:205], v[184:187], v[112:115]
	s_add_i32 m0, s25, 0x18000
	v_mfma_f32_16x16x32_bf16 v[108:111], v[206:209], v[184:187], v[108:111]
	global_load_lds_dwordx4 v2, s[26:27]
	v_mfma_f32_16x16x32_bf16 v[104:107], v[210:213], v[184:187], v[104:107]
	v_mfma_f32_16x16x32_bf16 v[100:103], v[214:217], v[184:187], v[100:103]
	s_add_i32 m0, s25, 0x1a000
	v_mfma_f32_16x16x32_bf16 v[96:99], v[202:205], v[188:191], v[96:99]
	global_load_lds_dwordx4 v134, s[26:27]
	v_mfma_f32_16x16x32_bf16 v[92:95], v[206:209], v[188:191], v[92:95]
	v_mfma_f32_16x16x32_bf16 v[88:91], v[210:213], v[188:191], v[88:91]
	s_add_i32 m0, s25, 0x8000
	v_mfma_f32_16x16x32_bf16 v[84:87], v[214:217], v[188:191], v[84:87]
	global_load_lds_dwordx4 v0, s[28:29]
	v_mfma_f32_16x16x32_bf16 v[80:83], v[202:205], v[192:195], v[80:83]
	v_mfma_f32_16x16x32_bf16 v[76:79], v[206:209], v[192:195], v[76:79]
	v_mfma_f32_16x16x32_bf16 v[72:75], v[210:213], v[192:195], v[72:75]
	v_mfma_f32_16x16x32_bf16 v[68:71], v[214:217], v[192:195], v[68:71]
	s_waitcnt lgkmcnt(0)
	v_mfma_f32_16x16x32_bf16 v[64:67], v[148:151], v[164:167], v[64:67]
	ds_read_b128 v[180:183], v146 offset:50176
	v_mfma_f32_16x16x32_bf16 v[60:63], v[152:155], v[164:167], v[60:63]
	ds_read_b128 v[184:187], v146 offset:52224
	v_mfma_f32_16x16x32_bf16 v[56:59], v[156:159], v[164:167], v[56:59]
	ds_read_b128 v[188:191], v146 offset:54272
	v_mfma_f32_16x16x32_bf16 v[52:55], v[160:163], v[164:167], v[52:55]
	ds_read_b128 v[192:195], v146 offset:56320
	v_mfma_f32_16x16x32_bf16 v[48:51], v[148:151], v[168:171], v[48:51]
	s_add_i32 m0, s25, 0xa000
	v_mfma_f32_16x16x32_bf16 v[44:47], v[152:155], v[168:171], v[44:47]
	global_load_lds_dwordx4 v132, s[28:29]
	v_mfma_f32_16x16x32_bf16 v[40:43], v[156:159], v[168:171], v[40:43]
	v_mfma_f32_16x16x32_bf16 v[36:39], v[160:163], v[168:171], v[36:39]
	s_add_u32 s98, s26, 0x80000
	s_addc_u32 s99, s27, 0
	s_add_i32 m0, s25, 0x1c000
	v_mfma_f32_16x16x32_bf16 v[32:35], v[148:151], v[172:175], v[32:35]
	global_load_lds_dwordx4 v2, s[98:99]
	v_mfma_f32_16x16x32_bf16 v[28:31], v[152:155], v[172:175], v[28:31]
	v_mfma_f32_16x16x32_bf16 v[24:27], v[156:159], v[172:175], v[24:27]
	s_add_i32 m0, s25, 0x1e000
	v_mfma_f32_16x16x32_bf16 v[20:23], v[160:163], v[172:175], v[20:23]
	global_load_lds_dwordx4 v134, s[98:99]
	v_mfma_f32_16x16x32_bf16 v[16:19], v[148:151], v[176:179], v[16:19]
	v_mfma_f32_16x16x32_bf16 v[12:15], v[152:155], v[176:179], v[12:15]
	v_mfma_f32_16x16x32_bf16 v[8:11], v[156:159], v[176:179], v[8:11]
	v_mfma_f32_16x16x32_bf16 v[4:7], v[160:163], v[176:179], v[4:7]
	s_waitcnt vmcnt(8) lgkmcnt(0)
	s_barrier
; #define LAS __attribute__((address_space(3)))
; #define PG8_STAGE(bufoff, gbase, voff) do { _Pragma("unroll") for (int _i = 0; _i < 2; ++_i) \
;         __builtin_amdgcn_global_load_lds((const unsigned*)((const char*)(gbase) + (voff)[_i]), (LAS unsigned*)(lds + (bufoff) + ldsw + _i * 8192), 16, 0, 0); } while (0)
; #define PG8_LDA(dst, b, h) do { _Pragma("unroll") for (int m = 0; m < 4; ++m) _Pragma("unroll") for (int k = 0; k < 2; ++k) dst[m][k] = *(const LAS bf16x8*)(lds + PG8_SA(b, h) + aoff + m * 2048 + k * 1024); } while (0)
; #define PG8_MMA(ai, bj, At, Bt) do { __builtin_amdgcn_s_setprio(1); _Pragma("unroll") for (int m = 0; m < 4; ++m) _Pragma("unroll") for (int n = 0; n < 2; ++n) _Pragma("unroll") for (int k = 0; k < 2; ++k) \
;         acc[ai][bj][m][n] = __builtin_amdgcn_mfma_f32_16x16x32_bf16(Bt[n][k], At[m][k], acc[ai][bj][m][n], 0, 0, 0); __builtin_amdgcn_s_setprio(0); } while (0)
; #define PG8_WAIT_V(n) asm volatile("s_waitcnt vmcnt(" #n ")" ::: "memory")
; #define PG8_WAIT_L(n) asm volatile("s_waitcnt lgkmcnt(" #n ")" ::: "memory")
; #define PG8_BAR __builtin_amdgcn_s_barrier()
; #define PG8_SCHED __builtin_amdgcn_sched_barrier(0)
; template <class Epi, int LDA, int LDB, int KK>
; __device__ __forceinline__ void gemm_phase(int wv, LAS unsigned char* lds, const Gemm g, const StaticOrder& S, const Epi& E) {
;     ...
;             PG8_LDA(At, 1, 1); PG8_STAGE(PG8_SA(1, 0), a3, voffA);
;             PG8_BAR; PG8_WAIT_L(0); PG8_MMA(1, 0, At, B0); PG8_BAR; PG8_SCHED;
;             PG8_STAGE(PG8_SB(1, 1), b3 + hstepB, voffB);
;             PG8_WAIT_V(6); PG8_BAR; PG8_MMA(1, 1, At, B1); PG8_BAR;
;           }
;           if constexpr (Epi::HAS_MID) { if (seg < Epi::NSEG - 1) E.mid(acc, cur, seg, wr, wc, fr, fq); }
;         }
;         E(acc, cur, wr, wc, fr, fq, (const LAS float*)(lds + 131072 + (ui % 3) * 1024));
;         if (!has_next) break;
	v_mfma_f32_16x16x32_bf16 v[64:67], v[202:205], v[180:183], v[64:67]
	ds_read_b128 v[148:151], v147 offset:0
	v_mfma_f32_16x16x32_bf16 v[60:63], v[206:209], v[180:183], v[60:63]
	ds_read_b128 v[152:155], v147 offset:2048
	v_mfma_f32_16x16x32_bf16 v[56:59], v[210:213], v[180:183], v[56:59]
	ds_read_b128 v[156:159], v147 offset:16384
	v_mfma_f32_16x16x32_bf16 v[52:55], v[214:217], v[180:183], v[52:55]
	ds_read_b128 v[160:163], v147 offset:18432
	v_mfma_f32_16x16x32_bf16 v[48:51], v[202:205], v[184:187], v[48:51]
	ds_read_b128 v[164:167], v146 offset:0
	v_mfma_f32_16x16x32_bf16 v[44:47], v[206:209], v[184:187], v[44:47]
	ds_read_b128 v[168:171], v146 offset:2048
	v_mfma_f32_16x16x32_bf16 v[40:43], v[210:213], v[184:187], v[40:43]
	ds_read_b128 v[172:175], v146 offset:4096
	v_mfma_f32_16x16x32_bf16 v[36:39], v[214:217], v[184:187], v[36:39]
	ds_read_b128 v[176:179], v146 offset:6144
	v_mfma_f32_16x16x32_bf16 v[32:35], v[202:205], v[188:191], v[32:35]
	s_add_u32 s98, s28, 0x80000
	s_addc_u32 s99, s29, 0
	s_add_i32 m0, s25, 0xc000
	v_mfma_f32_16x16x32_bf16 v[28:31], v[206:209], v[188:191], v[28:31]
	global_load_lds_dwordx4 v0, s[98:99]
	v_mfma_f32_16x16x32_bf16 v[24:27], v[210:213], v[188:191], v[24:27]
	v_mfma_f32_16x16x32_bf16 v[20:23], v[214:217], v[188:191], v[20:23]
	s_add_i32 m0, s25, 0xe000
	v_mfma_f32_16x16x32_bf16 v[16:19], v[202:205], v[192:195], v[16:19]
	global_load_lds_dwordx4 v132, s[98:99]
	v_mfma_f32_16x16x32_bf16 v[12:15], v[206:209], v[192:195], v[12:15]
	v_mfma_f32_16x16x32_bf16 v[8:11], v[210:213], v[192:195], v[8:11]
	v_mfma_f32_16x16x32_bf16 v[4:7], v[214:217], v[192:195], v[4:7]
	s_add_i32 s56, s56, 2
	s_add_u32 s47, s47, 0x100
	s_addc_u32 s55, s55, 0
	s_add_u32 s6, s6, 0x100
	s_addc_u32 s7, s7, 0
	s_cmp_gt_u32 s56, 29
	s_cbranch_scc0 .Lup_loop
	s_waitcnt lgkmcnt(0)
	s_cmp_eq_u32 s100, 0
	s_cbranch_scc1 .Lut_epi
	s_cmp_eq_u32 s100, 2
	s_cbranch_scc1 .Lut_owner
	s_sub_u32 s98, s81, 88
	s_cmp_lt_u32 s81, 88
	s_cselect_b32 s98, s81, s98
	s_lshl_b32 s98, s98, 18
	s_add_u32 s98, s98, 0x16c00000
	s_add_u32 s98, s10, s98
	s_addc_u32 s99, s11, 0
	v_mbcnt_lo_u32_b32 v148, -1, 0
	v_mbcnt_hi_u32_b32 v148, -1, v148
	v_lshl_or_b32 v148, s95, 6, v148
	v_lshlrev_b32_e32 v148, 4, v148
	global_store_dwordx4 v148, v[4:7], s[98:99] sc0 sc1
	v_add_u32_e32 v148, 0x2000, v148
	global_store_dwordx4 v148, v[8:11], s[98:99] sc0 sc1
	v_add_u32_e32 v148, 0x2000, v148
	global_store_dwordx4 v148, v[12:15], s[98:99] sc0 sc1
	v_add_u32_e32 v148, 0x2000, v148
	global_store_dwordx4 v148, v[16:19], s[98:99] sc0 sc1
	v_add_u32_e32 v148, 0x2000, v148
	global_store_dwordx4 v148, v[20:23], s[98:99] sc0 sc1
	v_add_u32_e32 v148, 0x2000, v148
	global_store_dwordx4 v148, v[24:27], s[98:99] sc0 sc1
	v_add_u32_e32 v148, 0x2000, v148
	global_store_dwordx4 v148, v[28:31], s[98:99] sc0 sc1
	v_add_u32_e32 v148, 0x2000, v148
	global_store_dwordx4 v148, v[32:35], s[98:99] sc0 sc1
	v_add_u32_e32 v148, 0x2000, v148
	global_store_dwordx4 v148, v[36:39], s[98:99] sc0 sc1
	v_add_u32_e32 v148, 0x2000, v148
	global_store_dwordx4 v148, v[40:43], s[98:99] sc0 sc1
	v_add_u32_e32 v148, 0x2000, v148
	global_store_dwordx4 v148, v[44:47], s[98:99] sc0 sc1
	v_add_u32_e32 v148, 0x2000, v148
	global_store_dwordx4 v148, v[48:51], s[98:99] sc0 sc1
	v_add_u32_e32 v148, 0x2000, v148
	global_store_dwordx4 v148, v[52:55], s[98:99] sc0 sc1
	v_add_u32_e32 v148, 0x2000, v148
	global_store_dwordx4 v148, v[56:59], s[98:99] sc0 sc1
	v_add_u32_e32 v148, 0x2000, v148
	global_store_dwordx4 v148, v[60:63], s[98:99] sc0 sc1
	v_add_u32_e32 v148, 0x2000, v148
	global_store_dwordx4 v148, v[64:67], s[98:99] sc0 sc1
	v_add_u32_e32 v148, 0x2000, v148
	global_store_dwordx4 v148, v[68:71], s[98:99] sc0 sc1
	v_add_u32_e32 v148, 0x2000, v148
	global_store_dwordx4 v148, v[72:75], s[98:99] sc0 sc1
	v_add_u32_e32 v148, 0x2000, v148
	global_store_dwordx4 v148, v[76:79], s[98:99] sc0 sc1
	v_add_u32_e32 v148, 0x2000, v148
	global_store_dwordx4 v148, v[80:83], s[98:99] sc0 sc1
	v_add_u32_e32 v148, 0x2000, v148
	global_store_dwordx4 v148, v[84:87], s[98:99] sc0 sc1
	v_add_u32_e32 v148, 0x2000, v148
	global_store_dwordx4 v148, v[88:91], s[98:99] sc0 sc1
	v_add_u32_e32 v148, 0x2000, v148
	global_store_dwordx4 v148, v[92:95], s[98:99] sc0 sc1
	v_add_u32_e32 v148, 0x2000, v148
	global_store_dwordx4 v148, v[96:99], s[98:99] sc0 sc1
	v_add_u32_e32 v148, 0x2000, v148
	global_store_dwordx4 v148, v[100:103], s[98:99] sc0 sc1
	v_add_u32_e32 v148, 0x2000, v148
	global_store_dwordx4 v148, v[104:107], s[98:99] sc0 sc1
	v_add_u32_e32 v148, 0x2000, v148
	global_store_dwordx4 v148, v[108:111], s[98:99] sc0 sc1
	v_add_u32_e32 v148, 0x2000, v148
	global_store_dwordx4 v148, v[112:115], s[98:99] sc0 sc1
	v_add_u32_e32 v148, 0x2000, v148
	global_store_dwordx4 v148, v[116:119], s[98:99] sc0 sc1
	v_add_u32_e32 v148, 0x2000, v148
	global_store_dwordx4 v148, v[120:123], s[98:99] sc0 sc1
	v_add_u32_e32 v148, 0x2000, v148
	global_store_dwordx4 v148, v[124:127], s[98:99] sc0 sc1
	v_add_u32_e32 v148, 0x2000, v148
	global_store_dwordx4 v148, v[128:131], s[98:99] sc0 sc1
	s_waitcnt vmcnt(0)
	s_barrier
	s_cmp_lg_u32 s95, 0
	s_cbranch_scc1 .Lut_p_done
	s_sub_u32 s98, s81, 88
	s_cmp_lt_u32 s81, 88
	s_cselect_b32 s98, s81, s98
	s_add_u32 s99, s98, 32
	s_cmp_lt_u32 s98, 64
	s_cselect_b32 s98, s98, s99
	s_lshl_b32 s98, s98, 2
	s_add_u32 s98, s98, 0x201da800
	s_add_u32 s98, s10, s98
	s_addc_u32 s99, s11, 0
	s_mov_b64 exec, 1
	v_mov_b32_e32 v148, 0
	v_mov_b32_e32 v149, 1
	global_atomic_add v148, v149, s[98:99]
	s_mov_b64 exec, -1

; #define PG8_STAGE(bufoff, gbase, voff) do { _Pragma("unroll") for (int _i = 0; _i < 2; ++_i) \
;         __builtin_amdgcn_global_load_lds((const unsigned*)((const char*)(gbase) + (voff)[_i]), (LAS unsigned*)(lds + (bufoff) + ldsw + _i * 8192), 16, 0, 0); } while (0)
; #define PG8_LDA(dst, b, h) do { _Pragma("unroll") for (int m = 0; m < 4; ++m) _Pragma("unroll") for (int k = 0; k < 2; ++k) dst[m][k] = *(const LAS bf16x8*)(lds + PG8_SA(b, h) + aoff + m * 2048 + k * 1024); } while (0)
; #define PG8_WAIT_V(n) asm volatile("s_waitcnt vmcnt(" #n ")" ::: "memory")
; #define PG8_BAR __builtin_amdgcn_s_barrier()
; template <class Epi, int LDA, int LDB, int KK>
; __device__ __forceinline__ void gemm_phase(int wv, LAS unsigned char* lds, const Gemm g, const StaticOrder& S, const Epi& E) {
;     ...
;           for (; t < tend; t += 2) {
;             const bool last = (t == nt - 2);
;             const char* a1 = cA + (size_t)(t + 1) * kstep;
;             const char* a2 = last ? nA : cA + (size_t)(t + 2) * kstep; const char* b2 = last ? nB : cB + (size_t)(t + 2) * kstep;
;             const char* a3 = a2 + kstep; const char* b3 = b2 + kstep;
;             PG8_LDB(B0, 0, 0); PG8_SCHED; PG8_LDA(At, 0, 0); PG8_STAGE(PG8_SA(1, 1), a1 + hstepA, voffA);
;             PG8_WAIT_L(8); PG8_BAR; PG8_WAIT_L(0); PG8_MMA(0, 0, At, B0); PG8_BAR; PG8_SCHED;
;             PG8_LDB(B1, 0, 1); PG8_STAGE(PG8_SB(0, 0), b2, voffB);
;             PG8_BAR; PG8_WAIT_L(0); PG8_MMA(0, 1, At, B1); PG8_BAR;
;             PG8_LDA(At, 0, 1); PG8_STAGE(PG8_SA(0, 0), a2, voffA);
;             PG8_BAR; PG8_WAIT_L(0); PG8_MMA(1, 0, At, B0); PG8_BAR; PG8_SCHED;
;             PG8_STAGE(PG8_SB(0, 1), b2 + hstepB, voffB);
;             PG8_WAIT_V(6); PG8_BAR; PG8_MMA(1, 1, At, B1); PG8_BAR;
;             PG8_LDB(B0, 1, 0); PG8_SCHED; PG8_LDA(At, 1, 0); PG8_STAGE(PG8_SA(0, 1), a2 + hstepA, voffA);
;             PG8_WAIT_L(8); PG8_BAR; PG8_WAIT_L(0); PG8_MMA(0, 0, At, B0); PG8_BAR; PG8_SCHED;
;             PG8_LDB(B1, 1, 1); PG8_STAGE(PG8_SB(1, 0), b3, voffB);
;             PG8_BAR; PG8_WAIT_L(0); PG8_MMA(0, 1, At, B1); PG8_BAR;
;             PG8_LDA(At, 1, 1); PG8_STAGE(PG8_SA(1, 0), a3, voffA);
;             PG8_BAR; PG8_WAIT_L(0); PG8_MMA(1, 0, At, B0); PG8_BAR; PG8_SCHED;
;             PG8_STAGE(PG8_SB(1, 1), b3 + hstepB, voffB);
;             PG8_WAIT_V(6); PG8_BAR; PG8_MMA(1, 1, At, B1); PG8_BAR;
.Ldown_loop:
	s_add_u32 s20, s18, 0x100
	s_addc_u32 s21, s19, 0
	s_cmpk_eq_i32 s56, 0x54
	s_cselect_b32 s25, s9, s21
	s_cselect_b32 s24, s8, s20
	s_cselect_b32 s23, s11, s55
	s_cselect_b32 s22, s10, s47
	s_waitcnt lgkmcnt(0)
	v_mfma_f32_16x16x32_bf16 v[128:131], v[132:135], v[148:151], v[128:131]
	ds_read_b128 v[202:205], v180 offset:1024
	v_mfma_f32_16x16x32_bf16 v[124:127], v[136:139], v[148:151], v[124:127]
	ds_read_b128 v[206:209], v180 offset:3072
	v_mfma_f32_16x16x32_bf16 v[120:123], v[140:143], v[148:151], v[120:123]
	ds_read_b128 v[210:213], v180 offset:17408
	v_mfma_f32_16x16x32_bf16 v[116:119], v[144:147], v[148:151], v[116:119]
	ds_read_b128 v[214:217], v180 offset:19456
	v_mfma_f32_16x16x32_bf16 v[112:115], v[132:135], v[152:155], v[112:115]
	ds_read_b128 v[164:167], v234 offset:1024
	v_mfma_f32_16x16x32_bf16 v[108:111], v[136:139], v[152:155], v[108:111]
	ds_read_b128 v[168:171], v234 offset:3072
	v_mfma_f32_16x16x32_bf16 v[104:107], v[140:143], v[152:155], v[104:107]
	ds_read_b128 v[172:175], v234 offset:5120
	v_mfma_f32_16x16x32_bf16 v[100:103], v[144:147], v[152:155], v[100:103]
	ds_read_b128 v[176:179], v234 offset:7168
	v_mfma_f32_16x16x32_bf16 v[96:99], v[132:135], v[156:159], v[96:99]
	v_mfma_f32_16x16x32_bf16 v[92:95], v[136:139], v[156:159], v[92:95]
	v_mfma_f32_16x16x32_bf16 v[88:91], v[140:143], v[156:159], v[88:91]
	v_mfma_f32_16x16x32_bf16 v[84:87], v[144:147], v[156:159], v[84:87]
	v_mfma_f32_16x16x32_bf16 v[80:83], v[132:135], v[160:163], v[80:83]
	v_mfma_f32_16x16x32_bf16 v[76:79], v[136:139], v[160:163], v[76:79]
	v_mfma_f32_16x16x32_bf16 v[72:75], v[140:143], v[160:163], v[72:75]
	v_mfma_f32_16x16x32_bf16 v[68:71], v[144:147], v[160:163], v[68:71]
	s_waitcnt vmcnt(8) lgkmcnt(0)
	s_barrier
	v_mfma_f32_16x16x32_bf16 v[128:131], v[202:205], v[164:167], v[128:131]
	ds_read_b128 v[148:151], v234 offset:16384
	v_mfma_f32_16x16x32_bf16 v[124:127], v[206:209], v[164:167], v[124:127]
	ds_read_b128 v[152:155], v234 offset:18432
	v_mfma_f32_16x16x32_bf16 v[120:123], v[210:213], v[164:167], v[120:123]
	ds_read_b128 v[156:159], v234 offset:20480
	v_mfma_f32_16x16x32_bf16 v[116:119], v[214:217], v[164:167], v[116:119]
	ds_read_b128 v[160:163], v234 offset:22528
	v_mfma_f32_16x16x32_bf16 v[112:115], v[202:205], v[168:171], v[112:115]
	s_add_i32 m0, s35, 0x10000
	v_mfma_f32_16x16x32_bf16 v[108:111], v[206:209], v[168:171], v[108:111]
	global_load_lds_dwordx4 v2, s[22:23]
	v_mfma_f32_16x16x32_bf16 v[104:107], v[210:213], v[168:171], v[104:107]
	v_mfma_f32_16x16x32_bf16 v[100:103], v[214:217], v[168:171], v[100:103]
	s_add_i32 m0, s35, 0x12000
	v_mfma_f32_16x16x32_bf16 v[96:99], v[202:205], v[172:175], v[96:99]
	global_load_lds_dwordx4 v190, s[22:23]
	v_mfma_f32_16x16x32_bf16 v[92:95], v[206:209], v[172:175], v[92:95]
	v_mfma_f32_16x16x32_bf16 v[88:91], v[210:213], v[172:175], v[88:91]
	s_mov_b32 m0, s35
	v_mfma_f32_16x16x32_bf16 v[84:87], v[214:217], v[172:175], v[84:87]
	global_load_lds_dwordx4 v0, s[24:25]
	v_mfma_f32_16x16x32_bf16 v[80:83], v[202:205], v[176:179], v[80:83]
	v_mfma_f32_16x16x32_bf16 v[76:79], v[206:209], v[176:179], v[76:79]
	v_mfma_f32_16x16x32_bf16 v[72:75], v[210:213], v[176:179], v[72:75]
	v_mfma_f32_16x16x32_bf16 v[68:71], v[214:217], v[176:179], v[68:71]
	s_waitcnt lgkmcnt(0)
	v_mfma_f32_16x16x32_bf16 v[64:67], v[132:135], v[148:151], v[64:67]
	ds_read_b128 v[164:167], v234 offset:17408
	v_mfma_f32_16x16x32_bf16 v[60:63], v[136:139], v[148:151], v[60:63]
	ds_read_b128 v[168:171], v234 offset:19456
	v_mfma_f32_16x16x32_bf16 v[56:59], v[140:143], v[148:151], v[56:59]
	ds_read_b128 v[172:175], v234 offset:21504
	v_mfma_f32_16x16x32_bf16 v[52:55], v[144:147], v[148:151], v[52:55]
	ds_read_b128 v[176:179], v234 offset:23552
	v_mfma_f32_16x16x32_bf16 v[48:51], v[132:135], v[152:155], v[48:51]
	s_add_i32 m0, s35, 0x2000
	v_mfma_f32_16x16x32_bf16 v[44:47], v[136:139], v[152:155], v[44:47]
	global_load_lds_dwordx4 v188, s[24:25]
	v_mfma_f32_16x16x32_bf16 v[40:43], v[140:143], v[152:155], v[40:43]
	v_mfma_f32_16x16x32_bf16 v[36:39], v[144:147], v[152:155], v[36:39]
	s_add_u32 s98, s22, 0x160000
	s_addc_u32 s99, s23, 0
	s_add_i32 m0, s35, 0x14000
	v_mfma_f32_16x16x32_bf16 v[32:35], v[132:135], v[156:159], v[32:35]
	global_load_lds_dwordx4 v2, s[98:99]
	v_mfma_f32_16x16x32_bf16 v[28:31], v[136:139], v[156:159], v[28:31]
	v_mfma_f32_16x16x32_bf16 v[24:27], v[140:143], v[156:159], v[24:27]
	s_add_i32 m0, s35, 0x16000
	v_mfma_f32_16x16x32_bf16 v[20:23], v[144:147], v[156:159], v[20:23]
	global_load_lds_dwordx4 v190, s[98:99]
	v_mfma_f32_16x16x32_bf16 v[16:19], v[132:135], v[160:163], v[16:19]
	v_mfma_f32_16x16x32_bf16 v[12:15], v[136:139], v[160:163], v[12:15]
	v_mfma_f32_16x16x32_bf16 v[8:11], v[140:143], v[160:163], v[8:11]
	v_mfma_f32_16x16x32_bf16 v[4:7], v[144:147], v[160:163], v[4:7]
	s_waitcnt vmcnt(8) lgkmcnt(0)
	s_barrier
; #define PG8_STAGE(bufoff, gbase, voff) do { _Pragma("unroll") for (int _i = 0; _i < 2; ++_i) \
;         __builtin_amdgcn_global_load_lds((const unsigned*)((const char*)(gbase) + (voff)[_i]), (LAS unsigned*)(lds + (bufoff) + ldsw + _i * 8192), 16, 0, 0); } while (0)
; #define PG8_LDA(dst, b, h) do { _Pragma("unroll") for (int m = 0; m < 4; ++m) _Pragma("unroll") for (int k = 0; k < 2; ++k) dst[m][k] = *(const LAS bf16x8*)(lds + PG8_SA(b, h) + aoff + m * 2048 + k * 1024); } while (0)
; #define PG8_LDB(dst, b, h) do { _Pragma("unroll") for (int n = 0; n < 2; ++n) _Pragma("unroll") for (int k = 0; k < 2; ++k) dst[n][k] = *(const LAS bf16x8*)(lds + PG8_SB(b, h) + boff + n * 2048 + k * 1024); } while (0)
; #define PG8_WAIT_V(n) asm volatile("s_waitcnt vmcnt(" #n ")" ::: "memory")
; #define PG8_WAIT_L(n) asm volatile("s_waitcnt lgkmcnt(" #n ")" ::: "memory")
; #define PG8_BAR __builtin_amdgcn_s_barrier()
; #define PG8_SCHED __builtin_amdgcn_sched_barrier(0)
; template <class Epi, int LDA, int LDB, int KK>
; __device__ __forceinline__ void gemm_phase(int wv, LAS unsigned char* lds, const Gemm g, const StaticOrder& S, const Epi& E) {
;     ...
;             PG8_LDB(B0, 0, 0); PG8_SCHED; PG8_LDA(At, 0, 0); PG8_STAGE(PG8_SA(1, 1), a1 + hstepA, voffA);
;             PG8_WAIT_L(8); PG8_BAR; PG8_WAIT_L(0); PG8_MMA(0, 0, At, B0); PG8_BAR; PG8_SCHED;
;             PG8_LDB(B1, 0, 1); PG8_STAGE(PG8_SB(0, 0), b2, voffB);
;             PG8_BAR; PG8_WAIT_L(0); PG8_MMA(0, 1, At, B1); PG8_BAR;
;             PG8_LDA(At, 0, 1); PG8_STAGE(PG8_SA(0, 0), a2, voffA);
;             PG8_BAR; PG8_WAIT_L(0); PG8_MMA(1, 0, At, B0); PG8_BAR; PG8_SCHED;
;             PG8_STAGE(PG8_SB(0, 1), b2 + hstepB, voffB);
;             PG8_WAIT_V(6); PG8_BAR; PG8_MMA(1, 1, At, B1); PG8_BAR;
;             PG8_LDB(B0, 1, 0); PG8_SCHED; PG8_LDA(At, 1, 0); PG8_STAGE(PG8_SA(0, 1), a2 + hstepA, voffA);
;             PG8_WAIT_L(8); PG8_BAR; PG8_WAIT_L(0); PG8_MMA(0, 0, At, B0); PG8_BAR; PG8_SCHED;
;             PG8_LDB(B1, 1, 1); PG8_STAGE(PG8_SB(1, 0), b3, voffB);
;             PG8_BAR; PG8_WAIT_L(0); PG8_MMA(0, 1, At, B1); PG8_BAR;
;             PG8_LDA(At, 1, 1); PG8_STAGE(PG8_SA(1, 0), a3, voffA);
;             PG8_BAR; PG8_WAIT_L(0); PG8_MMA(1, 0, At, B0); PG8_BAR; PG8_SCHED;
;             PG8_STAGE(PG8_SB(1, 1), b3 + hstepB, voffB);
;             PG8_WAIT_V(6); PG8_BAR; PG8_MMA(1, 1, At, B1); PG8_BAR;
	v_mfma_f32_16x16x32_bf16 v[64:67], v[202:205], v[164:167], v[64:67]
	ds_read_b128 v[132:135], v180 offset:32768
	v_mfma_f32_16x16x32_bf16 v[60:63], v[206:209], v[164:167], v[60:63]
	ds_read_b128 v[136:139], v180 offset:34816
	v_mfma_f32_16x16x32_bf16 v[56:59], v[210:213], v[164:167], v[56:59]
	ds_read_b128 v[140:143], v180 offset:49152
	v_mfma_f32_16x16x32_bf16 v[52:55], v[214:217], v[164:167], v[52:55]
	ds_read_b128 v[144:147], v180 offset:51200
	v_mfma_f32_16x16x32_bf16 v[48:51], v[202:205], v[168:171], v[48:51]
	ds_read_b128 v[148:151], v234 offset:32768
	v_mfma_f32_16x16x32_bf16 v[44:47], v[206:209], v[168:171], v[44:47]
	ds_read_b128 v[152:155], v234 offset:34816
	v_mfma_f32_16x16x32_bf16 v[40:43], v[210:213], v[168:171], v[40:43]
	ds_read_b128 v[156:159], v234 offset:36864
	v_mfma_f32_16x16x32_bf16 v[36:39], v[214:217], v[168:171], v[36:39]
	ds_read_b128 v[160:163], v234 offset:38912
	v_mfma_f32_16x16x32_bf16 v[32:35], v[202:205], v[172:175], v[32:35]
	s_add_u32 s98, s24, 0x2c0000
	s_addc_u32 s99, s25, 0
	s_add_i32 m0, s35, 0x4000
	v_mfma_f32_16x16x32_bf16 v[28:31], v[206:209], v[172:175], v[28:31]
	global_load_lds_dwordx4 v0, s[98:99]
	v_mfma_f32_16x16x32_bf16 v[24:27], v[210:213], v[172:175], v[24:27]
	v_mfma_f32_16x16x32_bf16 v[20:23], v[214:217], v[172:175], v[20:23]
	s_add_i32 m0, s35, 0x6000
	v_mfma_f32_16x16x32_bf16 v[16:19], v[202:205], v[176:179], v[16:19]
	global_load_lds_dwordx4 v188, s[98:99]
	v_mfma_f32_16x16x32_bf16 v[12:15], v[206:209], v[176:179], v[12:15]
	v_mfma_f32_16x16x32_bf16 v[8:11], v[210:213], v[176:179], v[8:11]
	v_mfma_f32_16x16x32_bf16 v[4:7], v[214:217], v[176:179], v[4:7]
	s_add_u32 s22, s22, 0x80
	s_addc_u32 s23, s23, 0
	s_add_u32 s24, s24, 0x80
	s_addc_u32 s25, s25, 0
	s_waitcnt lgkmcnt(0)
	v_mfma_f32_16x16x32_bf16 v[128:131], v[132:135], v[148:151], v[128:131]
	ds_read_b128 v[202:205], v180 offset:33792
	v_mfma_f32_16x16x32_bf16 v[124:127], v[136:139], v[148:151], v[124:127]
	ds_read_b128 v[206:209], v180 offset:35840
	v_mfma_f32_16x16x32_bf16 v[120:123], v[140:143], v[148:151], v[120:123]
	ds_read_b128 v[210:213], v180 offset:50176
	v_mfma_f32_16x16x32_bf16 v[116:119], v[144:147], v[148:151], v[116:119]
	ds_read_b128 v[214:217], v180 offset:52224
	v_mfma_f32_16x16x32_bf16 v[112:115], v[132:135], v[152:155], v[112:115]
	ds_read_b128 v[164:167], v234 offset:33792
	v_mfma_f32_16x16x32_bf16 v[108:111], v[136:139], v[152:155], v[108:111]
	ds_read_b128 v[168:171], v234 offset:35840
	v_mfma_f32_16x16x32_bf16 v[104:107], v[140:143], v[152:155], v[104:107]
	ds_read_b128 v[172:175], v234 offset:37888
	v_mfma_f32_16x16x32_bf16 v[100:103], v[144:147], v[152:155], v[100:103]
	ds_read_b128 v[176:179], v234 offset:39936
	v_mfma_f32_16x16x32_bf16 v[96:99], v[132:135], v[156:159], v[96:99]
	v_mfma_f32_16x16x32_bf16 v[92:95], v[136:139], v[156:159], v[92:95]
	v_mfma_f32_16x16x32_bf16 v[88:91], v[140:143], v[156:159], v[88:91]
	v_mfma_f32_16x16x32_bf16 v[84:87], v[144:147], v[156:159], v[84:87]
	v_mfma_f32_16x16x32_bf16 v[80:83], v[132:135], v[160:163], v[80:83]
	v_mfma_f32_16x16x32_bf16 v[76:79], v[136:139], v[160:163], v[76:79]
	v_mfma_f32_16x16x32_bf16 v[72:75], v[140:143], v[160:163], v[72:75]
	v_mfma_f32_16x16x32_bf16 v[68:71], v[144:147], v[160:163], v[68:71]
	s_waitcnt vmcnt(8) lgkmcnt(0)
	s_barrier
	v_mfma_f32_16x16x32_bf16 v[128:131], v[202:205], v[164:167], v[128:131]
	ds_read_b128 v[148:151], v234 offset:49152
	v_mfma_f32_16x16x32_bf16 v[124:127], v[206:209], v[164:167], v[124:127]
	ds_read_b128 v[152:155], v234 offset:51200
	v_mfma_f32_16x16x32_bf16 v[120:123], v[210:213], v[164:167], v[120:123]
	ds_read_b128 v[156:159], v234 offset:53248
	v_mfma_f32_16x16x32_bf16 v[116:119], v[214:217], v[164:167], v[116:119]
	ds_read_b128 v[160:163], v234 offset:55296
	v_mfma_f32_16x16x32_bf16 v[112:115], v[202:205], v[168:171], v[112:115]
	s_add_i32 m0, s35, 0x18000
	v_mfma_f32_16x16x32_bf16 v[108:111], v[206:209], v[168:171], v[108:111]
	global_load_lds_dwordx4 v2, s[22:23]
	v_mfma_f32_16x16x32_bf16 v[104:107], v[210:213], v[168:171], v[104:107]
	v_mfma_f32_16x16x32_bf16 v[100:103], v[214:217], v[168:171], v[100:103]
	s_add_i32 m0, s35, 0x1a000
	v_mfma_f32_16x16x32_bf16 v[96:99], v[202:205], v[172:175], v[96:99]
	global_load_lds_dwordx4 v190, s[22:23]
	v_mfma_f32_16x16x32_bf16 v[92:95], v[206:209], v[172:175], v[92:95]
	v_mfma_f32_16x16x32_bf16 v[88:91], v[210:213], v[172:175], v[88:91]
	s_add_i32 m0, s35, 0x8000
	v_mfma_f32_16x16x32_bf16 v[84:87], v[214:217], v[172:175], v[84:87]
	global_load_lds_dwordx4 v0, s[24:25]
	v_mfma_f32_16x16x32_bf16 v[80:83], v[202:205], v[176:179], v[80:83]
	v_mfma_f32_16x16x32_bf16 v[76:79], v[206:209], v[176:179], v[76:79]
	v_mfma_f32_16x16x32_bf16 v[72:75], v[210:213], v[176:179], v[72:75]
	v_mfma_f32_16x16x32_bf16 v[68:71], v[214:217], v[176:179], v[68:71]
	s_waitcnt lgkmcnt(0)
	v_mfma_f32_16x16x32_bf16 v[64:67], v[132:135], v[148:151], v[64:67]
	ds_read_b128 v[164:167], v234 offset:50176
	v_mfma_f32_16x16x32_bf16 v[60:63], v[136:139], v[148:151], v[60:63]
	ds_read_b128 v[168:171], v234 offset:52224
	v_mfma_f32_16x16x32_bf16 v[56:59], v[140:143], v[148:151], v[56:59]
	ds_read_b128 v[172:175], v234 offset:54272
	v_mfma_f32_16x16x32_bf16 v[52:55], v[144:147], v[148:151], v[52:55]
	ds_read_b128 v[176:179], v234 offset:56320
	v_mfma_f32_16x16x32_bf16 v[48:51], v[132:135], v[152:155], v[48:51]
	s_add_i32 m0, s35, 0xa000
	v_mfma_f32_16x16x32_bf16 v[44:47], v[136:139], v[152:155], v[44:47]
	global_load_lds_dwordx4 v188, s[24:25]
	v_mfma_f32_16x16x32_bf16 v[40:43], v[140:143], v[152:155], v[40:43]
	v_mfma_f32_16x16x32_bf16 v[36:39], v[144:147], v[152:155], v[36:39]
	s_add_u32 s98, s22, 0x160000
	s_addc_u32 s99, s23, 0
	s_add_i32 m0, s35, 0x1c000
	v_mfma_f32_16x16x32_bf16 v[32:35], v[132:135], v[156:159], v[32:35]
	global_load_lds_dwordx4 v2, s[98:99]
	v_mfma_f32_16x16x32_bf16 v[28:31], v[136:139], v[156:159], v[28:31]
	v_mfma_f32_16x16x32_bf16 v[24:27], v[140:143], v[156:159], v[24:27]
	s_add_i32 m0, s35, 0x1e000
	v_mfma_f32_16x16x32_bf16 v[20:23], v[144:147], v[156:159], v[20:23]
	global_load_lds_dwordx4 v190, s[98:99]
	v_mfma_f32_16x16x32_bf16 v[16:19], v[132:135], v[160:163], v[16:19]
	v_mfma_f32_16x16x32_bf16 v[12:15], v[136:139], v[160:163], v[12:15]
	v_mfma_f32_16x16x32_bf16 v[8:11], v[140:143], v[160:163], v[8:11]
	v_mfma_f32_16x16x32_bf16 v[4:7], v[144:147], v[160:163], v[4:7]
	s_waitcnt vmcnt(8) lgkmcnt(0)
	s_barrier
; #define LAS __attribute__((address_space(3)))
; #define PG8_STAGE(bufoff, gbase, voff) do { _Pragma("unroll") for (int _i = 0; _i < 2; ++_i) \
;         __builtin_amdgcn_global_load_lds((const unsigned*)((const char*)(gbase) + (voff)[_i]), (LAS unsigned*)(lds + (bufoff) + ldsw + _i * 8192), 16, 0, 0); } while (0)
; #define PG8_LDA(dst, b, h) do { _Pragma("unroll") for (int m = 0; m < 4; ++m) _Pragma("unroll") for (int k = 0; k < 2; ++k) dst[m][k] = *(const LAS bf16x8*)(lds + PG8_SA(b, h) + aoff + m * 2048 + k * 1024); } while (0)
; #define PG8_MMA(ai, bj, At, Bt) do { __builtin_amdgcn_s_setprio(1); _Pragma("unroll") for (int m = 0; m < 4; ++m) _Pragma("unroll") for (int n = 0; n < 2; ++n) _Pragma("unroll") for (int k = 0; k < 2; ++k) \
;         acc[ai][bj][m][n] = __builtin_amdgcn_mfma_f32_16x16x32_bf16(Bt[n][k], At[m][k], acc[ai][bj][m][n], 0, 0, 0); __builtin_amdgcn_s_setprio(0); } while (0)
; #define PG8_WAIT_V(n) asm volatile("s_waitcnt vmcnt(" #n ")" ::: "memory")
; #define PG8_WAIT_L(n) asm volatile("s_waitcnt lgkmcnt(" #n ")" ::: "memory")
; #define PG8_BAR __builtin_amdgcn_s_barrier()
; #define PG8_SCHED __builtin_amdgcn_sched_barrier(0)
; template <class Epi, int LDA, int LDB, int KK>
; __device__ __forceinline__ void gemm_phase(int wv, LAS unsigned char* lds, const Gemm g, const StaticOrder& S, const Epi& E) {
;     ...
;             PG8_LDA(At, 1, 1); PG8_STAGE(PG8_SA(1, 0), a3, voffA);
;             PG8_BAR; PG8_WAIT_L(0); PG8_MMA(1, 0, At, B0); PG8_BAR; PG8_SCHED;
;             PG8_STAGE(PG8_SB(1, 1), b3 + hstepB, voffB);
;             PG8_WAIT_V(6); PG8_BAR; PG8_MMA(1, 1, At, B1); PG8_BAR;
;           }
;           if constexpr (Epi::HAS_MID) { if (seg < Epi::NSEG - 1) E.mid(acc, cur, seg, wr, wc, fr, fq); }
;         }
;         E(acc, cur, wr, wc, fr, fq, (const LAS float*)(lds + 131072 + (ui % 3) * 1024));
;         if (!has_next) break;
	v_mfma_f32_16x16x32_bf16 v[64:67], v[202:205], v[164:167], v[64:67]
	ds_read_b128 v[132:135], v180 offset:0
	v_mfma_f32_16x16x32_bf16 v[60:63], v[206:209], v[164:167], v[60:63]
	ds_read_b128 v[136:139], v180 offset:2048
	v_mfma_f32_16x16x32_bf16 v[56:59], v[210:213], v[164:167], v[56:59]
	ds_read_b128 v[140:143], v180 offset:16384
	v_mfma_f32_16x16x32_bf16 v[52:55], v[214:217], v[164:167], v[52:55]
	ds_read_b128 v[144:147], v180 offset:18432
	v_mfma_f32_16x16x32_bf16 v[48:51], v[202:205], v[168:171], v[48:51]
	ds_read_b128 v[148:151], v234 offset:0
	v_mfma_f32_16x16x32_bf16 v[44:47], v[206:209], v[168:171], v[44:47]
	ds_read_b128 v[152:155], v234 offset:2048
	v_mfma_f32_16x16x32_bf16 v[40:43], v[210:213], v[168:171], v[40:43]
	ds_read_b128 v[156:159], v234 offset:4096
	v_mfma_f32_16x16x32_bf16 v[36:39], v[214:217], v[168:171], v[36:39]
	ds_read_b128 v[160:163], v234 offset:6144
	v_mfma_f32_16x16x32_bf16 v[32:35], v[202:205], v[172:175], v[32:35]
	s_add_u32 s98, s24, 0x2c0000
	s_addc_u32 s99, s25, 0
	s_add_i32 m0, s35, 0xc000
	v_mfma_f32_16x16x32_bf16 v[28:31], v[206:209], v[172:175], v[28:31]
	global_load_lds_dwordx4 v0, s[98:99]
	v_mfma_f32_16x16x32_bf16 v[24:27], v[210:213], v[172:175], v[24:27]
	v_mfma_f32_16x16x32_bf16 v[20:23], v[214:217], v[172:175], v[20:23]
	s_add_i32 m0, s35, 0xe000
	v_mfma_f32_16x16x32_bf16 v[16:19], v[202:205], v[176:179], v[16:19]
	global_load_lds_dwordx4 v188, s[98:99]
	v_mfma_f32_16x16x32_bf16 v[12:15], v[206:209], v[176:179], v[12:15]
	v_mfma_f32_16x16x32_bf16 v[8:11], v[210:213], v[176:179], v[8:11]
	v_mfma_f32_16x16x32_bf16 v[4:7], v[214:217], v[176:179], v[4:7]
	s_add_i32 s56, s56, 2
	s_add_u32 s47, s47, 0x100
	s_addc_u32 s55, s55, 0
	s_cmpk_gt_u32 s56, 0x55
	s_mov_b64 s[18:19], s[20:21]
	s_cbranch_scc0 .Ldown_loop
	s_waitcnt lgkmcnt(0)
	s_cmp_eq_u32 s100, 0
	s_cbranch_scc1 .Ldn_epi
	s_cmp_eq_u32 s100, 4
	s_cbranch_scc1 .Ldn_owner
	s_and_b32 s98, s81, 15
	s_mul_i32 s98, s98, 3
	s_add_u32 s98, s98, s100
	s_sub_u32 s98, s98, 1
	s_lshl_b32 s98, s98, 18
	s_add_u32 s98, s98, 0x1f000000
	s_add_u32 s98, s14, s98
	s_addc_u32 s99, s15, 0
	v_mbcnt_lo_u32_b32 v132, -1, 0
	v_mbcnt_hi_u32_b32 v132, -1, v132
	v_lshl_or_b32 v132, s95, 6, v132
	v_lshlrev_b32_e32 v132, 4, v132
	global_store_dwordx4 v132, v[4:7], s[98:99] sc0 sc1
	v_add_u32_e32 v132, 0x2000, v132
	global_store_dwordx4 v132, v[8:11], s[98:99] sc0 sc1
	v_add_u32_e32 v132, 0x2000, v132
	global_store_dwordx4 v132, v[12:15], s[98:99] sc0 sc1
	v_add_u32_e32 v132, 0x2000, v132
	global_store_dwordx4 v132, v[16:19], s[98:99] sc0 sc1
	v_add_u32_e32 v132, 0x2000, v132
	global_store_dwordx4 v132, v[20:23], s[98:99] sc0 sc1
	v_add_u32_e32 v132, 0x2000, v132
	global_store_dwordx4 v132, v[24:27], s[98:99] sc0 sc1
	v_add_u32_e32 v132, 0x2000, v132
	global_store_dwordx4 v132, v[28:31], s[98:99] sc0 sc1
	v_add_u32_e32 v132, 0x2000, v132
	global_store_dwordx4 v132, v[32:35], s[98:99] sc0 sc1
	v_add_u32_e32 v132, 0x2000, v132
	global_store_dwordx4 v132, v[36:39], s[98:99] sc0 sc1
	v_add_u32_e32 v132, 0x2000, v132
	global_store_dwordx4 v132, v[40:43], s[98:99] sc0 sc1
	v_add_u32_e32 v132, 0x2000, v132
	global_store_dwordx4 v132, v[44:47], s[98:99] sc0 sc1
	v_add_u32_e32 v132, 0x2000, v132
	global_store_dwordx4 v132, v[48:51], s[98:99] sc0 sc1
	v_add_u32_e32 v132, 0x2000, v132
	global_store_dwordx4 v132, v[52:55], s[98:99] sc0 sc1
	v_add_u32_e32 v132, 0x2000, v132
	global_store_dwordx4 v132, v[56:59], s[98:99] sc0 sc1
	v_add_u32_e32 v132, 0x2000, v132
	global_store_dwordx4 v132, v[60:63], s[98:99] sc0 sc1
	v_add_u32_e32 v132, 0x2000, v132
	global_store_dwordx4 v132, v[64:67], s[98:99] sc0 sc1
	v_add_u32_e32 v132, 0x2000, v132
	global_store_dwordx4 v132, v[68:71], s[98:99] sc0 sc1
	v_add_u32_e32 v132, 0x2000, v132
	global_store_dwordx4 v132, v[72:75], s[98:99] sc0 sc1
	v_add_u32_e32 v132, 0x2000, v132
	global_store_dwordx4 v132, v[76:79], s[98:99] sc0 sc1
	v_add_u32_e32 v132, 0x2000, v132
	global_store_dwordx4 v132, v[80:83], s[98:99] sc0 sc1
	v_add_u32_e32 v132, 0x2000, v132
	global_store_dwordx4 v132, v[84:87], s[98:99] sc0 sc1
	v_add_u32_e32 v132, 0x2000, v132
	global_store_dwordx4 v132, v[88:91], s[98:99] sc0 sc1
	v_add_u32_e32 v132, 0x2000, v132
	global_store_dwordx4 v132, v[92:95], s[98:99] sc0 sc1
	v_add_u32_e32 v132, 0x2000, v132
	global_store_dwordx4 v132, v[96:99], s[98:99] sc0 sc1
	v_add_u32_e32 v132, 0x2000, v132
	global_store_dwordx4 v132, v[100:103], s[98:99] sc0 sc1
	v_add_u32_e32 v132, 0x2000, v132
	global_store_dwordx4 v132, v[104:107], s[98:99] sc0 sc1
	v_add_u32_e32 v132, 0x2000, v132
	global_store_dwordx4 v132, v[108:111], s[98:99] sc0 sc1
	v_add_u32_e32 v132, 0x2000, v132
	global_store_dwordx4 v132, v[112:115], s[98:99] sc0 sc1
	v_add_u32_e32 v132, 0x2000, v132
	global_store_dwordx4 v132, v[116:119], s[98:99] sc0 sc1
	v_add_u32_e32 v132, 0x2000, v132
	global_store_dwordx4 v132, v[120:123], s[98:99] sc0 sc1
	v_add_u32_e32 v132, 0x2000, v132
	global_store_dwordx4 v132, v[124:127], s[98:99] sc0 sc1
	v_add_u32_e32 v132, 0x2000, v132
	global_store_dwordx4 v132, v[128:131], s[98:99] sc0 sc1
	s_waitcnt vmcnt(0)
	s_barrier
	s_cmp_lg_u32 s95, 0
	s_cbranch_scc1 .Ldn_p_done
	s_and_b32 s98, s81, 15
	s_lshl_b32 s98, s98, 2
	s_add_u32 s98, s98, 0x285da900
	s_add_u32 s98, s14, s98
	s_addc_u32 s99, s15, 0
	s_mov_b64 exec, 1
	v_mov_b32_e32 v132, 0
	v_mov_b32_e32 v133, 1
	global_atomic_add v132, v133, s[98:99]
	s_mov_b64 exec, -1
